# GEMM1 SwiGLU epilogue: v_pk_mul_f32 split into scalar v_mul_f32 pairs
# baseline (speedup 1.0000x reference)
; #define STG(P, GB) do { const char* _gb = (GB); \
;     _Pragma("unroll") for (int _i = 0; _i < 2; ++_i) { \
;       __builtin_amdgcn_global_load_lds((const unsigned*)(_gb + voff[_i]), \
;         (LAS unsigned*)((LAS char*)(P) + ldsw + _i * 8192), 16, 0, 0); } } while (0)
; #define LDA(dst, b, h) _Pragma("unroll") for (int m = 0; m < 4; ++m) _Pragma("unroll") for (int k = 0; k < 2; ++k) \
;     dst[m][k] = *(const LAS bf16x8*)((LAS char*)SA(b, h) + aoff + m * 2048 + k * 1024)
; #define LDB(dst, b, h) _Pragma("unroll") for (int n = 0; n < 2; ++n) _Pragma("unroll") for (int k = 0; k < 2; ++k) \
;     dst[n][k] = *(const LAS bf16x8*)((LAS char*)SB(b, h) + boff + n * 2048 + k * 1024)
; #define MMA(ai, bj, At_, Bt_) do { __builtin_amdgcn_s_setprio(1); \
;     _Pragma("unroll") for (int m = 0; m < 4; ++m) _Pragma("unroll") for (int n = 0; n < 2; ++n) _Pragma("unroll") for (int k = 0; k < 2; ++k) \
;       acc[ai][bj][m][n] = __builtin_amdgcn_mfma_f32_16x16x32_bf16(Bt_[n][k], At_[m][k], acc[ai][bj][m][n], 0, 0, 0); \
;     __builtin_amdgcn_s_setprio(0); } while (0)
; #define WAIT_L(n) asm volatile("s_waitcnt lgkmcnt(" #n ")" ::: "memory")
; #define BAR __builtin_amdgcn_s_barrier()
; #define SCHED __builtin_amdgcn_sched_barrier(0)
; __device__ __forceinline__ void gemm_phase(const bf16_t* __restrict__ A, const bf16_t* __restrict__ Bt, bf16_t* __restrict__ C, int M, int N, int K,
;                                            int ldc, const int EPI, char* smem, const int wid_u) {
;     ...
;       LDB(B0, 0, 0); SCHED; LDA(At, 0, 0); STG(SA(1, 1), a1 + hstep);
;       WAIT_L(8); BAR; WAIT_L(0); MMA(0, 0, At, B0); BAR; SCHED;
;       LDB(B1, 0, 1); STG(SB(0, 0), b2);
;       BAR; WAIT_L(0); MMA(0, 1, At, B1); BAR;
;       LDA(At, 0, 1); STG(SA(0, 0), a2);
;       BAR; WAIT_L(0); MMA(1, 0, At, B0); BAR; SCHED;
.LBB0_145:
	ds_read_b128 v[150:153], v146
	ds_read_b128 v[154:157], v146 offset:1024
	ds_read_b128 v[158:161], v146 offset:2048
	ds_read_b128 v[162:165], v146 offset:3072
	s_add_u32 s18, s16, 0x100
	s_addc_u32 s19, s17, 0
	s_cmp_eq_u32 s49, 12
	s_cselect_b32 s23, s44, s19
	s_cselect_b32 s22, s45, s18
	s_cselect_b32 s21, s11, s48
	s_cselect_b32 s20, s46, s47
	v_lshl_add_u64 v[142:143], s[16:17], 0, v[136:137]
	s_add_i32 m0, s28, 0xc000
	ds_read_b128 v[166:169], v147
	ds_read_b128 v[170:173], v147 offset:1024
	ds_read_b128 v[174:177], v147 offset:2048
	ds_read_b128 v[178:181], v147 offset:3072
	ds_read_b128 v[182:185], v147 offset:4096
	ds_read_b128 v[186:189], v147 offset:5120
	ds_read_b128 v[190:193], v147 offset:6144
	ds_read_b128 v[194:197], v147 offset:7168
	global_load_lds_dwordx4 v[142:143], off
	v_lshl_add_u64 v[142:143], s[16:17], 0, v[134:135]
	s_add_i32 m0, s28, 0xe000
	s_nop 0
	global_load_lds_dwordx4 v[142:143], off
	s_waitcnt lgkmcnt(8)
	s_barrier
	s_waitcnt lgkmcnt(0)
	s_waitcnt lgkmcnt(0)
	v_mfma_f32_16x16x32_bf16 v[124:127], v[150:153], v[166:169], v[124:127]
	v_mfma_f32_16x16x32_bf16 v[120:123], v[158:161], v[166:169], v[120:123]
	v_mfma_f32_16x16x32_bf16 v[108:111], v[150:153], v[174:177], v[108:111]
	v_mfma_f32_16x16x32_bf16 v[104:107], v[158:161], v[174:177], v[104:107]
	v_mfma_f32_16x16x32_bf16 v[92:95], v[150:153], v[182:185], v[92:95]
	v_mfma_f32_16x16x32_bf16 v[88:91], v[158:161], v[182:185], v[88:91]
	v_mfma_f32_16x16x32_bf16 v[76:79], v[150:153], v[190:193], v[76:79]
	v_mfma_f32_16x16x32_bf16 v[72:75], v[158:161], v[190:193], v[72:75]
	v_mfma_f32_16x16x32_bf16 v[124:127], v[154:157], v[170:173], v[124:127]
	v_mfma_f32_16x16x32_bf16 v[120:123], v[162:165], v[170:173], v[120:123]
	v_mfma_f32_16x16x32_bf16 v[108:111], v[154:157], v[178:181], v[108:111]
	v_mfma_f32_16x16x32_bf16 v[104:107], v[162:165], v[178:181], v[104:107]
	v_mfma_f32_16x16x32_bf16 v[92:95], v[154:157], v[186:189], v[92:95]
	v_mfma_f32_16x16x32_bf16 v[88:91], v[162:165], v[186:189], v[88:91]
	v_mfma_f32_16x16x32_bf16 v[76:79], v[154:157], v[194:197], v[76:79]
	v_mfma_f32_16x16x32_bf16 v[72:75], v[162:165], v[194:197], v[72:75]
	s_barrier
	s_add_i32 s16, s36, s27
	v_lshl_add_u64 v[142:143], s[20:21], 0, v[130:131]
	s_mov_b32 m0, s16
	ds_read_b128 v[198:201], v148
	ds_read_b128 v[202:205], v148 offset:1024
	ds_read_b128 v[206:209], v148 offset:2048
	ds_read_b128 v[210:213], v148 offset:3072
	global_load_lds_dwordx4 v[142:143], off
	v_lshl_add_u64 v[214:215], s[20:21], 0, v[128:129]
	s_add_i32 m0, s16, 0x2000
	s_nop 0
	global_load_lds_dwordx4 v[214:215], off
	s_barrier
	s_waitcnt lgkmcnt(0)
	s_waitcnt lgkmcnt(0)
	v_mfma_f32_16x16x32_bf16 v[116:119], v[198:201], v[166:169], v[116:119]
	v_mfma_f32_16x16x32_bf16 v[112:115], v[206:209], v[166:169], v[112:115]
	v_mfma_f32_16x16x32_bf16 v[100:103], v[198:201], v[174:177], v[100:103]
	v_mfma_f32_16x16x32_bf16 v[96:99], v[206:209], v[174:177], v[96:99]
	v_mfma_f32_16x16x32_bf16 v[84:87], v[198:201], v[182:185], v[84:87]
	v_mfma_f32_16x16x32_bf16 v[80:83], v[206:209], v[182:185], v[80:83]
	v_mfma_f32_16x16x32_bf16 v[68:71], v[198:201], v[190:193], v[68:71]
	v_mfma_f32_16x16x32_bf16 v[64:67], v[206:209], v[190:193], v[64:67]
	v_mfma_f32_16x16x32_bf16 v[116:119], v[202:205], v[170:173], v[116:119]
	v_mfma_f32_16x16x32_bf16 v[112:115], v[210:213], v[170:173], v[112:115]
	v_mfma_f32_16x16x32_bf16 v[100:103], v[202:205], v[178:181], v[100:103]
	v_mfma_f32_16x16x32_bf16 v[96:99], v[210:213], v[178:181], v[96:99]
	v_mfma_f32_16x16x32_bf16 v[84:87], v[202:205], v[186:189], v[84:87]
	v_mfma_f32_16x16x32_bf16 v[80:83], v[210:213], v[186:189], v[80:83]
	v_mfma_f32_16x16x32_bf16 v[68:71], v[202:205], v[194:197], v[68:71]
	v_mfma_f32_16x16x32_bf16 v[64:67], v[210:213], v[194:197], v[64:67]
	s_mov_b32 m0, s28
	v_lshl_add_u64 v[216:217], s[22:23], 0, v[130:131]
	s_barrier
	ds_read_b128 v[166:169], v147 offset:16384
	ds_read_b128 v[170:173], v147 offset:17408
	ds_read_b128 v[174:177], v147 offset:18432
	ds_read_b128 v[178:181], v147 offset:19456
	ds_read_b128 v[182:185], v147 offset:20480
	ds_read_b128 v[186:189], v147 offset:21504
	ds_read_b128 v[190:193], v147 offset:22528
	ds_read_b128 v[194:197], v147 offset:23552
	global_load_lds_dwordx4 v[216:217], off
	v_lshl_add_u64 v[218:219], s[22:23], 0, v[128:129]
	s_mov_b32 m0, s29
	s_nop 0
	global_load_lds_dwordx4 v[218:219], off
	s_barrier
	s_waitcnt lgkmcnt(0)
	s_waitcnt lgkmcnt(0)
	v_mfma_f32_16x16x32_bf16 v[60:63], v[150:153], v[166:169], v[60:63]
	v_mfma_f32_16x16x32_bf16 v[56:59], v[158:161], v[166:169], v[56:59]
	v_mfma_f32_16x16x32_bf16 v[44:47], v[150:153], v[174:177], v[44:47]
	v_mfma_f32_16x16x32_bf16 v[40:43], v[158:161], v[174:177], v[40:43]
	v_mfma_f32_16x16x32_bf16 v[28:31], v[150:153], v[182:185], v[28:31]
	v_mfma_f32_16x16x32_bf16 v[24:27], v[158:161], v[182:185], v[24:27]
	v_mfma_f32_16x16x32_bf16 v[12:15], v[150:153], v[190:193], v[12:15]
	v_mfma_f32_16x16x32_bf16 v[8:11], v[158:161], v[190:193], v[8:11]
	v_mfma_f32_16x16x32_bf16 v[60:63], v[154:157], v[170:173], v[60:63]
	v_mfma_f32_16x16x32_bf16 v[56:59], v[162:165], v[170:173], v[56:59]
	v_mfma_f32_16x16x32_bf16 v[44:47], v[154:157], v[178:181], v[44:47]
	v_mfma_f32_16x16x32_bf16 v[40:43], v[162:165], v[178:181], v[40:43]
	v_mfma_f32_16x16x32_bf16 v[28:31], v[154:157], v[186:189], v[28:31]
	v_mfma_f32_16x16x32_bf16 v[24:27], v[162:165], v[186:189], v[24:27]
	v_mfma_f32_16x16x32_bf16 v[12:15], v[154:157], v[194:197], v[12:15]
	v_mfma_f32_16x16x32_bf16 v[8:11], v[162:165], v[194:197], v[8:11]
	s_barrier
; #define STG(P, GB) do { const char* _gb = (GB); \
;     _Pragma("unroll") for (int _i = 0; _i < 2; ++_i) { \
;       __builtin_amdgcn_global_load_lds((const unsigned*)(_gb + voff[_i]), \
;         (LAS unsigned*)((LAS char*)(P) + ldsw + _i * 8192), 16, 0, 0); } } while (0)
; #define LDA(dst, b, h) _Pragma("unroll") for (int m = 0; m < 4; ++m) _Pragma("unroll") for (int k = 0; k < 2; ++k) \
;     dst[m][k] = *(const LAS bf16x8*)((LAS char*)SA(b, h) + aoff + m * 2048 + k * 1024)
; #define LDB(dst, b, h) _Pragma("unroll") for (int n = 0; n < 2; ++n) _Pragma("unroll") for (int k = 0; k < 2; ++k) \
;     dst[n][k] = *(const LAS bf16x8*)((LAS char*)SB(b, h) + boff + n * 2048 + k * 1024)
; #define MMA(ai, bj, At_, Bt_) do { __builtin_amdgcn_s_setprio(1); \
;     _Pragma("unroll") for (int m = 0; m < 4; ++m) _Pragma("unroll") for (int n = 0; n < 2; ++n) _Pragma("unroll") for (int k = 0; k < 2; ++k) \
;       acc[ai][bj][m][n] = __builtin_amdgcn_mfma_f32_16x16x32_bf16(Bt_[n][k], At_[m][k], acc[ai][bj][m][n], 0, 0, 0); \
;     __builtin_amdgcn_s_setprio(0); } while (0)
; #define WAIT_V(n) asm volatile("s_waitcnt vmcnt(" #n ")" ::: "memory")
; #define WAIT_L(n) asm volatile("s_waitcnt lgkmcnt(" #n ")" ::: "memory")
; #define BAR __builtin_amdgcn_s_barrier()
; #define SCHED __builtin_amdgcn_sched_barrier(0)
; __device__ __forceinline__ void gemm_phase(const bf16_t* __restrict__ A, const bf16_t* __restrict__ Bt, bf16_t* __restrict__ C, int M, int N, int K,
;                                            int ldc, const int EPI, char* smem, const int wid_u) {
;     ...
;       STG(SB(0, 1), b2 + hstep);
;       WAIT_V(6); BAR; MMA(1, 1, At, B1); BAR;
;       LDB(B0, 1, 0); SCHED; LDA(At, 1, 0); STG(SA(0, 1), a2 + hstep);
;       WAIT_L(8); BAR; WAIT_L(0); MMA(0, 0, At, B0); BAR; SCHED;
;       LDB(B1, 1, 1); STG(SB(1, 0), b3);
;       BAR; WAIT_L(0); MMA(0, 1, At, B1); BAR;
;       LDA(At, 1, 1); STG(SA(1, 0), a3);
;       BAR; WAIT_L(0); MMA(1, 0, At, B0); BAR; SCHED;
	s_add_u32 s16, s20, 0x40000
	s_addc_u32 s17, s21, 0
	s_add_i32 s50, s37, s27
	v_lshl_add_u64 v[150:151], s[16:17], 0, v[130:131]
	s_mov_b32 m0, s50
	s_nop 0
	global_load_lds_dwordx4 v[150:151], off
	v_lshl_add_u64 v[150:151], s[16:17], 0, v[128:129]
	s_add_i32 m0, s50, 0x2000
	s_nop 0
	global_load_lds_dwordx4 v[150:151], off
	s_waitcnt vmcnt(6)
	s_barrier
	v_mfma_f32_16x16x32_bf16 v[52:55], v[198:201], v[166:169], v[52:55]
	v_mfma_f32_16x16x32_bf16 v[48:51], v[206:209], v[166:169], v[48:51]
	v_mfma_f32_16x16x32_bf16 v[36:39], v[198:201], v[174:177], v[36:39]
	v_mfma_f32_16x16x32_bf16 v[32:35], v[206:209], v[174:177], v[32:35]
	v_mfma_f32_16x16x32_bf16 v[20:23], v[198:201], v[182:185], v[20:23]
	v_mfma_f32_16x16x32_bf16 v[16:19], v[206:209], v[182:185], v[16:19]
	v_mfma_f32_16x16x32_bf16 v[4:7], v[198:201], v[190:193], v[4:7]
	v_mfma_f32_16x16x32_bf16 v[0:3], v[206:209], v[190:193], v[0:3]
	v_mfma_f32_16x16x32_bf16 v[52:55], v[202:205], v[170:173], v[52:55]
	v_mfma_f32_16x16x32_bf16 v[48:51], v[210:213], v[170:173], v[48:51]
	v_mfma_f32_16x16x32_bf16 v[36:39], v[202:205], v[178:181], v[36:39]
	v_mfma_f32_16x16x32_bf16 v[32:35], v[210:213], v[178:181], v[32:35]
	v_mfma_f32_16x16x32_bf16 v[20:23], v[202:205], v[186:189], v[20:23]
	v_mfma_f32_16x16x32_bf16 v[16:19], v[210:213], v[186:189], v[16:19]
	v_mfma_f32_16x16x32_bf16 v[4:7], v[202:205], v[194:197], v[4:7]
	v_mfma_f32_16x16x32_bf16 v[0:3], v[210:213], v[194:197], v[0:3]
	s_add_i32 s50, 0, 0x18000
	v_add_u32_e32 v149, s50, v145
	s_barrier
	ds_read_b128 v[150:153], v149
	ds_read_b128 v[154:157], v149 offset:1024
	ds_read_b128 v[158:161], v149 offset:2048
	ds_read_b128 v[162:165], v149 offset:3072
	s_add_u32 s16, s22, 0x40000
	s_addc_u32 s17, s23, 0
	s_mov_b32 m0, s30
	v_lshl_add_u64 v[198:199], s[16:17], 0, v[130:131]
	ds_read_b128 v[166:169], v147 offset:32768
	ds_read_b128 v[170:173], v147 offset:33792
	ds_read_b128 v[174:177], v147 offset:34816
	ds_read_b128 v[178:181], v147 offset:35840
	ds_read_b128 v[182:185], v147 offset:36864
	ds_read_b128 v[186:189], v147 offset:37888
	ds_read_b128 v[190:193], v147 offset:38912
	ds_read_b128 v[194:197], v147 offset:39936
	global_load_lds_dwordx4 v[198:199], off
	v_lshl_add_u64 v[198:199], s[16:17], 0, v[128:129]
	s_mov_b32 m0, s31
	s_nop 0
	global_load_lds_dwordx4 v[198:199], off
	s_waitcnt lgkmcnt(8)
	s_barrier
	s_waitcnt lgkmcnt(0)
	s_waitcnt lgkmcnt(0)
	v_mfma_f32_16x16x32_bf16 v[124:127], v[150:153], v[166:169], v[124:127]
	v_mfma_f32_16x16x32_bf16 v[120:123], v[158:161], v[166:169], v[120:123]
	v_mfma_f32_16x16x32_bf16 v[108:111], v[150:153], v[174:177], v[108:111]
	v_mfma_f32_16x16x32_bf16 v[104:107], v[158:161], v[174:177], v[104:107]
	v_mfma_f32_16x16x32_bf16 v[92:95], v[150:153], v[182:185], v[92:95]
	v_mfma_f32_16x16x32_bf16 v[88:91], v[158:161], v[182:185], v[88:91]
	v_mfma_f32_16x16x32_bf16 v[76:79], v[150:153], v[190:193], v[76:79]
	v_mfma_f32_16x16x32_bf16 v[72:75], v[158:161], v[190:193], v[72:75]
	v_mfma_f32_16x16x32_bf16 v[124:127], v[154:157], v[170:173], v[124:127]
	v_mfma_f32_16x16x32_bf16 v[120:123], v[162:165], v[170:173], v[120:123]
	v_mfma_f32_16x16x32_bf16 v[108:111], v[154:157], v[178:181], v[108:111]
	v_mfma_f32_16x16x32_bf16 v[104:107], v[162:165], v[178:181], v[104:107]
	v_mfma_f32_16x16x32_bf16 v[92:95], v[154:157], v[186:189], v[92:95]
	v_mfma_f32_16x16x32_bf16 v[88:91], v[162:165], v[186:189], v[88:91]
	v_mfma_f32_16x16x32_bf16 v[76:79], v[154:157], v[194:197], v[76:79]
	v_mfma_f32_16x16x32_bf16 v[72:75], v[162:165], v[194:197], v[72:75]
	s_barrier
	s_add_i32 s22, 0, 0x1c000
	s_add_i32 s16, s50, s27
	v_add_u32_e32 v149, s22, v145
	v_lshl_add_u64 v[142:143], v[142:143], 0, s[6:7]
	s_mov_b32 m0, s16
	ds_read_b128 v[198:201], v149
	ds_read_b128 v[202:205], v149 offset:1024
	ds_read_b128 v[206:209], v149 offset:2048
	ds_read_b128 v[210:213], v149 offset:3072
	global_load_lds_dwordx4 v[142:143], off
	v_lshl_add_u64 v[142:143], v[214:215], 0, s[6:7]
	s_add_i32 m0, s16, 0x2000
	s_nop 0
	global_load_lds_dwordx4 v[142:143], off
	s_barrier
	s_waitcnt lgkmcnt(0)
	s_waitcnt lgkmcnt(0)
	v_mfma_f32_16x16x32_bf16 v[116:119], v[198:201], v[166:169], v[116:119]
	v_mfma_f32_16x16x32_bf16 v[112:115], v[206:209], v[166:169], v[112:115]
	v_mfma_f32_16x16x32_bf16 v[100:103], v[198:201], v[174:177], v[100:103]
	v_mfma_f32_16x16x32_bf16 v[96:99], v[206:209], v[174:177], v[96:99]
	v_mfma_f32_16x16x32_bf16 v[84:87], v[198:201], v[182:185], v[84:87]
	v_mfma_f32_16x16x32_bf16 v[80:83], v[206:209], v[182:185], v[80:83]
	v_mfma_f32_16x16x32_bf16 v[68:71], v[198:201], v[190:193], v[68:71]
	v_mfma_f32_16x16x32_bf16 v[64:67], v[206:209], v[190:193], v[64:67]
	v_mfma_f32_16x16x32_bf16 v[116:119], v[202:205], v[170:173], v[116:119]
	v_mfma_f32_16x16x32_bf16 v[112:115], v[210:213], v[170:173], v[112:115]
	v_mfma_f32_16x16x32_bf16 v[100:103], v[202:205], v[178:181], v[100:103]
	v_mfma_f32_16x16x32_bf16 v[96:99], v[210:213], v[178:181], v[96:99]
	v_mfma_f32_16x16x32_bf16 v[84:87], v[202:205], v[186:189], v[84:87]
	v_mfma_f32_16x16x32_bf16 v[80:83], v[210:213], v[186:189], v[80:83]
	v_mfma_f32_16x16x32_bf16 v[68:71], v[202:205], v[194:197], v[68:71]
	v_mfma_f32_16x16x32_bf16 v[64:67], v[210:213], v[194:197], v[64:67]
	s_mov_b32 m0, s34
	v_lshl_add_u64 v[142:143], v[216:217], 0, s[6:7]
	s_barrier
	ds_read_b128 v[166:169], v147 offset:49152
	ds_read_b128 v[170:173], v147 offset:50176
	ds_read_b128 v[174:177], v147 offset:51200
	ds_read_b128 v[178:181], v147 offset:52224
	ds_read_b128 v[182:185], v147 offset:53248
	ds_read_b128 v[186:189], v147 offset:54272
	ds_read_b128 v[190:193], v147 offset:55296
	ds_read_b128 v[194:197], v147 offset:56320
	global_load_lds_dwordx4 v[142:143], off
	v_lshl_add_u64 v[142:143], v[218:219], 0, s[6:7]
	s_mov_b32 m0, s35
	s_nop 0
	global_load_lds_dwordx4 v[142:143], off
	s_barrier
; #define STG(P, GB) do { const char* _gb = (GB); \
;     _Pragma("unroll") for (int _i = 0; _i < 2; ++_i) { \
;       __builtin_amdgcn_global_load_lds((const unsigned*)(_gb + voff[_i]), \
;         (LAS unsigned*)((LAS char*)(P) + ldsw + _i * 8192), 16, 0, 0); } } while (0)
; #define MMA(ai, bj, At_, Bt_) do { __builtin_amdgcn_s_setprio(1); \
;     _Pragma("unroll") for (int m = 0; m < 4; ++m) _Pragma("unroll") for (int n = 0; n < 2; ++n) _Pragma("unroll") for (int k = 0; k < 2; ++k) \
;       acc[ai][bj][m][n] = __builtin_amdgcn_mfma_f32_16x16x32_bf16(Bt_[n][k], At_[m][k], acc[ai][bj][m][n], 0, 0, 0); \
;     __builtin_amdgcn_s_setprio(0); } while (0)
; #define WAIT_V(n) asm volatile("s_waitcnt vmcnt(" #n ")" ::: "memory")
; #define BAR __builtin_amdgcn_s_barrier()
; __device__ __forceinline__ void gemm_phase(const bf16_t* __restrict__ A, const bf16_t* __restrict__ Bt, bf16_t* __restrict__ C, int M, int N, int K,
;                                            int ldc, const int EPI, char* smem, const int wid_u) {
;     ...
;       STG(SB(1, 1), b3 + hstep);
;       WAIT_V(6); BAR; MMA(1, 1, At, B1); BAR;
;     ...
;             float o[8];
; #pragma unroll
;             for (int n = 0; n < 2; ++n) {
;               const f32x4 a = acc[ai][0][m][n], b = acc[ai][1][m][n];
; #pragma unroll
;               for (int j = 0; j < 4; ++j) o[n * 4 + j] = a[j] * __builtin_amdgcn_rcpf(1.f + __expf(-a[j])) * b[j];
;             }
;             *(uint4*)(C + row * ldc + (bcol >> 1) + wc * 32 + fq * 8) = pack8(o);
	s_waitcnt lgkmcnt(0)
	s_waitcnt lgkmcnt(0)
	v_mfma_f32_16x16x32_bf16 v[60:63], v[150:153], v[166:169], v[60:63]
	v_mfma_f32_16x16x32_bf16 v[56:59], v[158:161], v[166:169], v[56:59]
	v_mfma_f32_16x16x32_bf16 v[44:47], v[150:153], v[174:177], v[44:47]
	v_mfma_f32_16x16x32_bf16 v[40:43], v[158:161], v[174:177], v[40:43]
	v_mfma_f32_16x16x32_bf16 v[28:31], v[150:153], v[182:185], v[28:31]
	v_mfma_f32_16x16x32_bf16 v[24:27], v[158:161], v[182:185], v[24:27]
	v_mfma_f32_16x16x32_bf16 v[12:15], v[150:153], v[190:193], v[12:15]
	v_mfma_f32_16x16x32_bf16 v[8:11], v[158:161], v[190:193], v[8:11]
	v_mfma_f32_16x16x32_bf16 v[60:63], v[154:157], v[170:173], v[60:63]
	v_mfma_f32_16x16x32_bf16 v[56:59], v[162:165], v[170:173], v[56:59]
	v_mfma_f32_16x16x32_bf16 v[44:47], v[154:157], v[178:181], v[44:47]
	v_mfma_f32_16x16x32_bf16 v[40:43], v[162:165], v[178:181], v[40:43]
	v_mfma_f32_16x16x32_bf16 v[28:31], v[154:157], v[186:189], v[28:31]
	v_mfma_f32_16x16x32_bf16 v[24:27], v[162:165], v[186:189], v[24:27]
	v_mfma_f32_16x16x32_bf16 v[12:15], v[154:157], v[194:197], v[12:15]
	v_mfma_f32_16x16x32_bf16 v[8:11], v[162:165], v[194:197], v[8:11]
	s_barrier
	s_add_u32 s16, s20, 0x40080
	s_addc_u32 s17, s21, 0
	s_add_i32 s20, s22, s27
	v_lshl_add_u64 v[142:143], s[16:17], 0, v[130:131]
	s_mov_b32 m0, s20
	s_nop 0
	global_load_lds_dwordx4 v[142:143], off
	v_lshl_add_u64 v[142:143], s[16:17], 0, v[128:129]
	s_add_i32 m0, s20, 0x2000
	s_nop 0
	global_load_lds_dwordx4 v[142:143], off
	s_waitcnt vmcnt(6)
	s_barrier
	v_mfma_f32_16x16x32_bf16 v[52:55], v[198:201], v[166:169], v[52:55]
	v_mfma_f32_16x16x32_bf16 v[48:51], v[206:209], v[166:169], v[48:51]
	v_mfma_f32_16x16x32_bf16 v[36:39], v[198:201], v[174:177], v[36:39]
	v_mfma_f32_16x16x32_bf16 v[32:35], v[206:209], v[174:177], v[32:35]
	v_mfma_f32_16x16x32_bf16 v[20:23], v[198:201], v[182:185], v[20:23]
	v_mfma_f32_16x16x32_bf16 v[16:19], v[206:209], v[182:185], v[16:19]
	v_mfma_f32_16x16x32_bf16 v[4:7], v[198:201], v[190:193], v[4:7]
	v_mfma_f32_16x16x32_bf16 v[0:3], v[206:209], v[190:193], v[0:3]
	v_mfma_f32_16x16x32_bf16 v[52:55], v[202:205], v[170:173], v[52:55]
	v_mfma_f32_16x16x32_bf16 v[48:51], v[210:213], v[170:173], v[48:51]
	v_mfma_f32_16x16x32_bf16 v[36:39], v[202:205], v[178:181], v[36:39]
	v_mfma_f32_16x16x32_bf16 v[32:35], v[210:213], v[178:181], v[32:35]
	v_mfma_f32_16x16x32_bf16 v[20:23], v[202:205], v[186:189], v[20:23]
	v_mfma_f32_16x16x32_bf16 v[16:19], v[210:213], v[186:189], v[16:19]
	v_mfma_f32_16x16x32_bf16 v[4:7], v[202:205], v[194:197], v[4:7]
	v_mfma_f32_16x16x32_bf16 v[0:3], v[210:213], v[194:197], v[0:3]
	s_add_i32 s49, s49, 2
	s_add_u32 s47, s47, 0x100
	s_addc_u32 s48, s48, 0
	s_cmp_gt_u32 s49, 13
	s_mov_b64 s[16:17], s[18:19]
	s_barrier
	s_cbranch_scc0 .LBB0_145
	v_mul_f32_e32 v142, 0xbfb8aa3b, v124
	v_exp_f32_e32 v142, v142
	v_mul_f32_e32 v143, 0xbfb8aa3b, v125
	v_exp_f32_e32 v143, v143
	s_lshl_b32 s16, s40, 8
	v_add_f32_e32 v142, 1.0, v142
	v_rcp_f32_e32 v150, v142
	v_add_f32_e32 v142, 1.0, v143
	v_rcp_f32_e32 v151, v142
	s_mov_b32 s17, s9
	v_lshl_add_u32 v149, s41, 8, v144
	v_lshl_add_u64 v[142:143], v[132:133], 0, s[16:17]
	v_mul_f32_e64 v124, v124, v150
	v_mul_f32_e64 v125, v125, v151
	v_mul_f32_e32 v150, 0xbfb8aa3b, v126
	v_mul_f32_e32 v151, 0xbfb8aa3b, v127
	v_exp_f32_e32 v150, v150
	v_exp_f32_e32 v151, v151
	v_mul_f32_e64 v116, v124, v116
	v_mul_f32_e64 v117, v125, v117
	s_and_b64 vcc, exec, s[2:3]
	v_add_f32_e32 v124, 1.0, v150
	v_add_f32_e32 v125, 1.0, v151
	v_mul_f32_e32 v150, 0xbfb8aa3b, v120
	v_mul_f32_e32 v151, 0xbfb8aa3b, v121
	v_rcp_f32_e32 v124, v124
	v_rcp_f32_e32 v125, v125
	v_exp_f32_e32 v150, v150
	v_exp_f32_e32 v151, v151
	s_mov_b32 s41, s8
	v_mul_f32_e64 v124, v126, v124
	v_mul_f32_e64 v125, v127, v125
	v_add_f32_e32 v126, 1.0, v150
	v_add_f32_e32 v127, 1.0, v151
	v_mul_f32_e32 v150, 0xbfb8aa3b, v122
	v_mul_f32_e32 v151, 0xbfb8aa3b, v123
	v_exp_f32_e32 v150, v150
	v_exp_f32_e32 v151, v151
	v_rcp_f32_e32 v126, v126
	v_rcp_f32_e32 v127, v127
	v_add_f32_e32 v150, 1.0, v150
	v_add_f32_e32 v151, 1.0, v151
	v_rcp_f32_e32 v150, v150
	v_rcp_f32_e32 v151, v151
	v_mul_f32_e64 v120, v120, v126
	v_mul_f32_e64 v121, v121, v127
	v_mul_f32_e64 v118, v124, v118
	v_mul_f32_e64 v119, v125, v119
	v_mul_f32_e64 v120, v120, v112
	v_mul_f32_e64 v121, v121, v113
	v_mul_f32_e64 v112, v122, v150
	v_mul_f32_e64 v113, v123, v151
	s_mov_b32 s40, s10
	v_mul_f32_e64 v122, v112, v114
	v_mul_f32_e64 v123, v113, v115
	v_mul_f32_e32 v115, 0xbfb8aa3b, v108
	v_cvt_pk_bf16_f32 v112, v116, v117
	v_exp_f32_e32 v116, v115
	v_mul_f32_e32 v115, 0xbfb8aa3b, v109
	v_exp_f32_e32 v117, v115
	v_cvt_pk_bf16_f32 v113, v118, v119
	v_cvt_pk_bf16_f32 v114, v120, v121
	v_cvt_pk_bf16_f32 v115, v122, v123
	v_add_f32_e32 v116, 1.0, v116
	v_add_f32_e32 v117, 1.0, v117
	v_mad_i64_i32 v[118:119], s[16:17], v149, s38, v[142:143]
	v_rcp_f32_e32 v116, v116
	v_rcp_f32_e32 v117, v117
	global_store_dwordx4 v[118:119], v[112:115], off
	s_mov_b64 s[18:19], s[14:15]
	v_mul_f32_e64 v108, v108, v116
	v_mul_f32_e64 v109, v109, v117
	v_mul_f32_e32 v112, 0xbfb8aa3b, v110
	v_mul_f32_e32 v113, 0xbfb8aa3b, v111
	v_exp_f32_e32 v112, v112
	v_exp_f32_e32 v113, v113
	v_mul_f32_e64 v100, v108, v100
	v_mul_f32_e64 v101, v109, v101
	v_or_b32_e32 v114, 16, v149
	v_add_f32_e32 v108, 1.0, v112
	v_add_f32_e32 v109, 1.0, v113
	v_mul_f32_e32 v112, 0xbfb8aa3b, v104
	v_mul_f32_e32 v113, 0xbfb8aa3b, v105
	v_rcp_f32_e32 v108, v108
	v_rcp_f32_e32 v109, v109
	v_exp_f32_e32 v112, v112
	v_exp_f32_e32 v113, v113
	v_mul_f32_e64 v108, v110, v108
	v_mul_f32_e64 v109, v111, v109
	v_add_f32_e32 v110, 1.0, v112
	v_add_f32_e32 v111, 1.0, v113
; __device__ __forceinline__ void gemm_phase(const bf16_t* __restrict__ A, const bf16_t* __restrict__ Bt, bf16_t* __restrict__ C, int M, int N, int K,
;                                            int ldc, const int EPI, char* smem, const int wid_u) {
;     ...
;             float o[8];
; #pragma unroll
;             for (int n = 0; n < 2; ++n) {
;               const f32x4 a = acc[ai][0][m][n], b = acc[ai][1][m][n];
; #pragma unroll
;               for (int j = 0; j < 4; ++j) o[n * 4 + j] = a[j] * __builtin_amdgcn_rcpf(1.f + __expf(-a[j])) * b[j];
;             }
;             *(uint4*)(C + row * ldc + (bcol >> 1) + wc * 32 + fq * 8) = pack8(o);
	v_mul_f32_e32 v112, 0xbfb8aa3b, v106
	v_mul_f32_e32 v113, 0xbfb8aa3b, v107
	v_exp_f32_e32 v112, v112
	v_exp_f32_e32 v113, v113
	v_rcp_f32_e32 v110, v110
	v_rcp_f32_e32 v111, v111
	v_add_f32_e32 v112, 1.0, v112
	v_add_f32_e32 v113, 1.0, v113
	v_rcp_f32_e32 v112, v112
	v_rcp_f32_e32 v113, v113
	v_mul_f32_e64 v104, v104, v110
	v_mul_f32_e64 v105, v105, v111
	v_mul_f32_e64 v102, v108, v102
	v_mul_f32_e64 v103, v109, v103
	v_mul_f32_e64 v104, v104, v96
	v_mul_f32_e64 v105, v105, v97
	v_mul_f32_e64 v96, v106, v112
	v_mul_f32_e64 v97, v107, v113
	s_nop 0
	v_mul_f32_e64 v106, v96, v98
	v_mul_f32_e64 v107, v97, v99
	v_mul_f32_e32 v99, 0xbfb8aa3b, v92
	v_cvt_pk_bf16_f32 v96, v100, v101
	v_exp_f32_e32 v100, v99
	v_mul_f32_e32 v99, 0xbfb8aa3b, v93
	v_exp_f32_e32 v101, v99
	v_cvt_pk_bf16_f32 v97, v102, v103
	v_cvt_pk_bf16_f32 v98, v104, v105
	v_cvt_pk_bf16_f32 v99, v106, v107
	v_add_f32_e32 v100, 1.0, v100
	v_add_f32_e32 v101, 1.0, v101
	v_mad_i64_i32 v[102:103], s[16:17], v114, s38, v[142:143]
	v_rcp_f32_e32 v100, v100
	v_rcp_f32_e32 v101, v101
	global_store_dwordx4 v[102:103], v[96:99], off
	v_mul_f32_e64 v92, v92, v100
	v_mul_f32_e64 v93, v93, v101
	s_nop 0
	v_mul_f32_e32 v96, 0xbfb8aa3b, v94
	v_mul_f32_e32 v97, 0xbfb8aa3b, v95
	v_exp_f32_e32 v96, v96
	v_exp_f32_e32 v97, v97
	v_mul_f32_e64 v84, v92, v84
	v_mul_f32_e64 v85, v93, v85
	v_or_b32_e32 v98, 32, v149
	v_add_f32_e32 v92, 1.0, v96
	v_add_f32_e32 v93, 1.0, v97
	v_mul_f32_e32 v96, 0xbfb8aa3b, v88
	v_mul_f32_e32 v97, 0xbfb8aa3b, v89
	v_rcp_f32_e32 v92, v92
	v_rcp_f32_e32 v93, v93
	v_exp_f32_e32 v96, v96
	v_exp_f32_e32 v97, v97
	v_mul_f32_e64 v92, v94, v92
	v_mul_f32_e64 v93, v95, v93
	v_add_f32_e32 v94, 1.0, v96
	v_add_f32_e32 v95, 1.0, v97
	v_mul_f32_e32 v96, 0xbfb8aa3b, v90
	v_mul_f32_e32 v97, 0xbfb8aa3b, v91
	v_exp_f32_e32 v96, v96
	v_exp_f32_e32 v97, v97
	v_rcp_f32_e32 v94, v94
	v_rcp_f32_e32 v95, v95
	v_add_f32_e32 v96, 1.0, v96
	v_add_f32_e32 v97, 1.0, v97
	v_rcp_f32_e32 v96, v96
	v_rcp_f32_e32 v97, v97
	v_mul_f32_e64 v88, v88, v94
	v_mul_f32_e64 v89, v89, v95
	v_mul_f32_e64 v86, v92, v86
	v_mul_f32_e64 v87, v93, v87
	v_mul_f32_e64 v88, v88, v80
	v_mul_f32_e64 v89, v89, v81
	v_mul_f32_e64 v80, v90, v96
	v_mul_f32_e64 v81, v91, v97
	s_nop 0
	v_mul_f32_e64 v90, v80, v82
	v_mul_f32_e64 v91, v81, v83
	v_mul_f32_e32 v83, 0xbfb8aa3b, v76
	v_cvt_pk_bf16_f32 v80, v84, v85
	v_exp_f32_e32 v84, v83
	v_mul_f32_e32 v83, 0xbfb8aa3b, v77
	v_exp_f32_e32 v85, v83
	v_cvt_pk_bf16_f32 v81, v86, v87
	v_cvt_pk_bf16_f32 v82, v88, v89
	v_cvt_pk_bf16_f32 v83, v90, v91
	v_add_f32_e32 v84, 1.0, v84
	v_add_f32_e32 v85, 1.0, v85
	v_mad_i64_i32 v[86:87], s[16:17], v98, s38, v[142:143]
	v_rcp_f32_e32 v84, v84
	v_rcp_f32_e32 v85, v85
	global_store_dwordx4 v[86:87], v[80:83], off
	v_mul_f32_e64 v76, v76, v84
	v_mul_f32_e64 v77, v77, v85
	s_nop 0
	v_mul_f32_e32 v80, 0xbfb8aa3b, v78
	v_mul_f32_e32 v81, 0xbfb8aa3b, v79
	v_exp_f32_e32 v80, v80
	v_exp_f32_e32 v81, v81
	v_mul_f32_e64 v68, v76, v68
	v_mul_f32_e64 v69, v77, v69
	v_or_b32_e32 v82, 48, v149
	v_add_f32_e32 v76, 1.0, v80
	v_add_f32_e32 v77, 1.0, v81
	v_mul_f32_e32 v80, 0xbfb8aa3b, v72
	v_mul_f32_e32 v81, 0xbfb8aa3b, v73
	v_rcp_f32_e32 v76, v76
	v_rcp_f32_e32 v77, v77
	v_exp_f32_e32 v80, v80
	v_exp_f32_e32 v81, v81
	v_mul_f32_e64 v76, v78, v76
	v_mul_f32_e64 v77, v79, v77
	v_add_f32_e32 v78, 1.0, v80
	v_add_f32_e32 v79, 1.0, v81
	v_mul_f32_e32 v80, 0xbfb8aa3b, v74
	v_mul_f32_e32 v81, 0xbfb8aa3b, v75
	v_exp_f32_e32 v80, v80
	v_exp_f32_e32 v81, v81
	v_rcp_f32_e32 v78, v78
	v_rcp_f32_e32 v79, v79
	v_add_f32_e32 v80, 1.0, v80
	v_add_f32_e32 v81, 1.0, v81
	v_rcp_f32_e32 v80, v80
	v_rcp_f32_e32 v81, v81
	v_mul_f32_e64 v72, v72, v78
	v_mul_f32_e64 v73, v73, v79
	v_mul_f32_e64 v70, v76, v70
	v_mul_f32_e64 v71, v77, v71
	v_mul_f32_e64 v72, v72, v64
	v_mul_f32_e64 v73, v73, v65
	v_mul_f32_e64 v64, v74, v80
	v_mul_f32_e64 v65, v75, v81
	s_nop 0
	v_mul_f32_e64 v74, v64, v66
	v_mul_f32_e64 v75, v65, v67
	v_mul_f32_e32 v67, 0xbfb8aa3b, v60
	v_cvt_pk_bf16_f32 v64, v68, v69
	v_exp_f32_e32 v68, v67
	v_mul_f32_e32 v67, 0xbfb8aa3b, v61
	v_exp_f32_e32 v69, v67
	v_cvt_pk_bf16_f32 v65, v70, v71
	v_cvt_pk_bf16_f32 v66, v72, v73
	v_cvt_pk_bf16_f32 v67, v74, v75
	v_add_f32_e32 v68, 1.0, v68
	v_add_f32_e32 v69, 1.0, v69
	v_mad_i64_i32 v[70:71], s[16:17], v82, s38, v[142:143]
	v_rcp_f32_e32 v68, v68
	v_rcp_f32_e32 v69, v69
	global_store_dwordx4 v[70:71], v[64:67], off
	v_mul_f32_e64 v60, v60, v68
	v_mul_f32_e64 v61, v61, v69
	s_nop 0
	v_mul_f32_e32 v64, 0xbfb8aa3b, v62
	v_mul_f32_e32 v65, 0xbfb8aa3b, v63
	v_exp_f32_e32 v64, v64
	v_exp_f32_e32 v65, v65
	v_mul_f32_e64 v52, v60, v52
	v_mul_f32_e64 v53, v61, v53
	v_add_u32_e32 v66, 0x80, v149
	v_add_f32_e32 v60, 1.0, v64
	v_add_f32_e32 v61, 1.0, v65
	v_mul_f32_e32 v64, 0xbfb8aa3b, v56
	v_mul_f32_e32 v65, 0xbfb8aa3b, v57
	v_rcp_f32_e32 v60, v60
	v_rcp_f32_e32 v61, v61
	v_exp_f32_e32 v64, v64
	v_exp_f32_e32 v65, v65
	v_mul_f32_e64 v60, v62, v60
	v_mul_f32_e64 v61, v63, v61
	v_add_f32_e32 v62, 1.0, v64
	v_add_f32_e32 v63, 1.0, v65
	v_mul_f32_e32 v64, 0xbfb8aa3b, v58
	v_mul_f32_e32 v65, 0xbfb8aa3b, v59
	v_exp_f32_e32 v64, v64
	v_exp_f32_e32 v65, v65
	v_rcp_f32_e32 v62, v62
	v_rcp_f32_e32 v63, v63
	v_add_f32_e32 v64, 1.0, v64
	v_add_f32_e32 v65, 1.0, v65
	v_rcp_f32_e32 v64, v64
	v_rcp_f32_e32 v65, v65
	v_mul_f32_e64 v56, v56, v62
	v_mul_f32_e64 v57, v57, v63
	v_mul_f32_e64 v54, v60, v54
	v_mul_f32_e64 v55, v61, v55
	v_mul_f32_e64 v56, v56, v48
; #define WAIT_V(n) asm volatile("s_waitcnt vmcnt(" #n ")" ::: "memory")
; #define BAR __builtin_amdgcn_s_barrier()
; __device__ __forceinline__ void gemm_phase(const bf16_t* __restrict__ A, const bf16_t* __restrict__ Bt, bf16_t* __restrict__ C, int M, int N, int K,
;                                            int ldc, const int EPI, char* smem, const int wid_u) {
;     ...
;             float o[8];
; #pragma unroll
;             for (int n = 0; n < 2; ++n) {
;               const f32x4 a = acc[ai][0][m][n], b = acc[ai][1][m][n];
; #pragma unroll
;               for (int j = 0; j < 4; ++j) o[n * 4 + j] = a[j] * __builtin_amdgcn_rcpf(1.f + __expf(-a[j])) * b[j];
;             }
;             *(uint4*)(C + row * ldc + (bcol >> 1) + wc * 32 + fq * 8) = pack8(o);
;           }
;         }
;     }
;     if (!has_next) break;
; #pragma unroll
;     for (int a = 0; a < 2; ++a)
; #pragma unroll
;       for (int b = 0; b < 2; ++b)
; #pragma unroll
;         for (int m = 0; m < 4; ++m)
; #pragma unroll
;           for (int n = 0; n < 2; ++n) acc[a][b][m][n] = (f32x4){0.f, 0.f, 0.f, 0.f};
;     pm = npm; pn = npn; cA = nA; cB = nB; ++ui;
;   }
;   WAIT_V(0);
;   if (wr == 0) BAR;
;   BAR;
	v_mul_f32_e64 v57, v57, v49
	v_mul_f32_e64 v48, v58, v64
	v_mul_f32_e64 v49, v59, v65
	s_nop 0
	v_mul_f32_e64 v58, v48, v50
	v_mul_f32_e64 v59, v49, v51
	v_mul_f32_e32 v51, 0xbfb8aa3b, v44
	v_cvt_pk_bf16_f32 v48, v52, v53
	v_exp_f32_e32 v52, v51
	v_mul_f32_e32 v51, 0xbfb8aa3b, v45
	v_exp_f32_e32 v53, v51
	v_cvt_pk_bf16_f32 v49, v54, v55
	v_cvt_pk_bf16_f32 v50, v56, v57
	v_cvt_pk_bf16_f32 v51, v58, v59
	v_add_f32_e32 v52, 1.0, v52
	v_add_f32_e32 v53, 1.0, v53
	v_mad_i64_i32 v[54:55], s[16:17], v66, s38, v[142:143]
	v_rcp_f32_e32 v52, v52
	v_rcp_f32_e32 v53, v53
	global_store_dwordx4 v[54:55], v[48:51], off
	v_mul_f32_e64 v44, v44, v52
	v_mul_f32_e64 v45, v45, v53
	s_nop 0
	v_mul_f32_e32 v48, 0xbfb8aa3b, v46
	v_mul_f32_e32 v49, 0xbfb8aa3b, v47
	v_exp_f32_e32 v48, v48
	v_exp_f32_e32 v49, v49
	v_mul_f32_e64 v36, v44, v36
	v_mul_f32_e64 v37, v45, v37
	v_add_u32_e32 v50, 0x90, v149
	v_add_f32_e32 v44, 1.0, v48
	v_add_f32_e32 v45, 1.0, v49
	v_mul_f32_e32 v48, 0xbfb8aa3b, v40
	v_mul_f32_e32 v49, 0xbfb8aa3b, v41
	v_rcp_f32_e32 v44, v44
	v_rcp_f32_e32 v45, v45
	v_exp_f32_e32 v48, v48
	v_exp_f32_e32 v49, v49
	v_mul_f32_e64 v44, v46, v44
	v_mul_f32_e64 v45, v47, v45
	v_add_f32_e32 v46, 1.0, v48
	v_add_f32_e32 v47, 1.0, v49
	v_mul_f32_e32 v48, 0xbfb8aa3b, v42
	v_mul_f32_e32 v49, 0xbfb8aa3b, v43
	v_exp_f32_e32 v48, v48
	v_exp_f32_e32 v49, v49
	v_rcp_f32_e32 v46, v46
	v_rcp_f32_e32 v47, v47
	v_add_f32_e32 v48, 1.0, v48
	v_add_f32_e32 v49, 1.0, v49
	v_rcp_f32_e32 v48, v48
	v_rcp_f32_e32 v49, v49
	v_mul_f32_e64 v40, v40, v46
	v_mul_f32_e64 v41, v41, v47
	v_mul_f32_e64 v38, v44, v38
	v_mul_f32_e64 v39, v45, v39
	v_mul_f32_e64 v40, v40, v32
	v_mul_f32_e64 v41, v41, v33
	v_mul_f32_e64 v32, v42, v48
	v_mul_f32_e64 v33, v43, v49
	s_nop 0
	v_mul_f32_e64 v42, v32, v34
	v_mul_f32_e64 v43, v33, v35
	v_mul_f32_e32 v35, 0xbfb8aa3b, v28
	v_cvt_pk_bf16_f32 v32, v36, v37
	v_exp_f32_e32 v36, v35
	v_mul_f32_e32 v35, 0xbfb8aa3b, v29
	v_exp_f32_e32 v37, v35
	v_cvt_pk_bf16_f32 v33, v38, v39
	v_cvt_pk_bf16_f32 v34, v40, v41
	v_cvt_pk_bf16_f32 v35, v42, v43
	v_add_f32_e32 v36, 1.0, v36
	v_add_f32_e32 v37, 1.0, v37
	v_mad_i64_i32 v[38:39], s[16:17], v50, s38, v[142:143]
	v_rcp_f32_e32 v36, v36
	v_rcp_f32_e32 v37, v37
	global_store_dwordx4 v[38:39], v[32:35], off
	v_mul_f32_e64 v28, v28, v36
	v_mul_f32_e64 v29, v29, v37
	s_nop 0
	v_mul_f32_e32 v32, 0xbfb8aa3b, v30
	v_mul_f32_e32 v33, 0xbfb8aa3b, v31
	v_exp_f32_e32 v32, v32
	v_exp_f32_e32 v33, v33
	v_mul_f32_e64 v20, v28, v20
	v_mul_f32_e64 v21, v29, v21
	v_add_u32_e32 v34, 0xa0, v149
	v_add_f32_e32 v28, 1.0, v32
	v_add_f32_e32 v29, 1.0, v33
	v_mul_f32_e32 v32, 0xbfb8aa3b, v24
	v_mul_f32_e32 v33, 0xbfb8aa3b, v25
	v_rcp_f32_e32 v28, v28
	v_rcp_f32_e32 v29, v29
	v_exp_f32_e32 v32, v32
	v_exp_f32_e32 v33, v33
	v_mul_f32_e64 v28, v30, v28
	v_mul_f32_e64 v29, v31, v29
	v_add_f32_e32 v30, 1.0, v32
	v_add_f32_e32 v31, 1.0, v33
	v_mul_f32_e32 v32, 0xbfb8aa3b, v26
	v_mul_f32_e32 v33, 0xbfb8aa3b, v27
	v_exp_f32_e32 v32, v32
	v_exp_f32_e32 v33, v33
	v_rcp_f32_e32 v30, v30
	v_rcp_f32_e32 v31, v31
	v_add_f32_e32 v32, 1.0, v32
	v_add_f32_e32 v33, 1.0, v33
	v_rcp_f32_e32 v32, v32
	v_rcp_f32_e32 v33, v33
	v_mul_f32_e64 v24, v24, v30
	v_mul_f32_e64 v25, v25, v31
	v_mul_f32_e64 v22, v28, v22
	v_mul_f32_e64 v23, v29, v23
	v_mul_f32_e64 v24, v24, v16
	v_mul_f32_e64 v25, v25, v17
	v_mul_f32_e64 v16, v26, v32
	v_mul_f32_e64 v17, v27, v33
	s_nop 0
	v_mul_f32_e64 v26, v16, v18
	v_mul_f32_e64 v27, v17, v19
	v_mul_f32_e32 v19, 0xbfb8aa3b, v12
	v_cvt_pk_bf16_f32 v16, v20, v21
	v_exp_f32_e32 v20, v19
	v_mul_f32_e32 v19, 0xbfb8aa3b, v13
	v_exp_f32_e32 v21, v19
	v_cvt_pk_bf16_f32 v17, v22, v23
	v_cvt_pk_bf16_f32 v18, v24, v25
	v_cvt_pk_bf16_f32 v19, v26, v27
	v_add_f32_e32 v20, 1.0, v20
	v_add_f32_e32 v21, 1.0, v21
	v_mad_i64_i32 v[22:23], s[16:17], v34, s38, v[142:143]
	v_rcp_f32_e32 v20, v20
	v_rcp_f32_e32 v21, v21
	global_store_dwordx4 v[22:23], v[16:19], off
	v_mul_f32_e64 v12, v12, v20
	v_mul_f32_e64 v13, v13, v21
	s_nop 0
	v_mul_f32_e32 v16, 0xbfb8aa3b, v14
	v_mul_f32_e32 v17, 0xbfb8aa3b, v15
	v_exp_f32_e32 v16, v16
	v_exp_f32_e32 v17, v17
	v_mul_f32_e64 v4, v12, v4
	v_mul_f32_e64 v5, v13, v5
	v_add_u32_e32 v18, 0xb0, v149
	v_add_f32_e32 v12, 1.0, v16
	v_add_f32_e32 v13, 1.0, v17
	v_mul_f32_e32 v16, 0xbfb8aa3b, v8
	v_mul_f32_e32 v17, 0xbfb8aa3b, v9
	v_rcp_f32_e32 v12, v12
	v_rcp_f32_e32 v13, v13
	v_exp_f32_e32 v16, v16
	v_exp_f32_e32 v17, v17
	v_mul_f32_e64 v12, v14, v12
	v_mul_f32_e64 v13, v15, v13
	v_add_f32_e32 v14, 1.0, v16
	v_add_f32_e32 v15, 1.0, v17
	v_mul_f32_e32 v16, 0xbfb8aa3b, v10
	v_mul_f32_e32 v17, 0xbfb8aa3b, v11
	v_exp_f32_e32 v16, v16
	v_exp_f32_e32 v17, v17
	v_rcp_f32_e32 v14, v14
	v_rcp_f32_e32 v15, v15
	v_add_f32_e32 v16, 1.0, v16
	v_add_f32_e32 v17, 1.0, v17
	v_rcp_f32_e32 v16, v16
	v_rcp_f32_e32 v17, v17
	v_mul_f32_e64 v8, v8, v14
	v_mul_f32_e64 v9, v9, v15
	v_mul_f32_e64 v6, v12, v6
	v_mul_f32_e64 v7, v13, v7
	v_mul_f32_e64 v8, v8, v0
	v_mul_f32_e64 v9, v9, v1
	v_mul_f32_e64 v0, v10, v16
	v_mul_f32_e64 v1, v11, v17
	s_nop 0
	v_mul_f32_e64 v10, v0, v2
	v_mul_f32_e64 v11, v1, v3
	v_cvt_pk_bf16_f32 v0, v4, v5
	v_mad_i64_i32 v[4:5], s[16:17], v18, s38, v[142:143]
	v_cvt_pk_bf16_f32 v1, v6, v7
	v_cvt_pk_bf16_f32 v2, v8, v9
	v_cvt_pk_bf16_f32 v3, v10, v11
	s_mov_b64 s[16:17], s[12:13]
	global_store_dwordx4 v[4:5], v[0:3], off
	s_cbranch_vccz .LBB0_142
	s_waitcnt vmcnt(0)
	s_cmpk_gt_u32 s24, 0xff
	s_cbranch_scc1 .LBB0_149
	s_barrier

; #define STG(P, GB) do { const char* _gb = (GB); \
;     _Pragma("unroll") for (int _i = 0; _i < 2; ++_i) { \
;       __builtin_amdgcn_global_load_lds((const unsigned*)(_gb + voff[_i]), \
;         (LAS unsigned*)((LAS char*)(P) + ldsw + _i * 8192), 16, 0, 0); } } while (0)
; #define LDA(dst, b, h) _Pragma("unroll") for (int m = 0; m < 4; ++m) _Pragma("unroll") for (int k = 0; k < 2; ++k) \
;     dst[m][k] = *(const LAS bf16x8*)((LAS char*)SA(b, h) + aoff + m * 2048 + k * 1024)
; #define LDB(dst, b, h) _Pragma("unroll") for (int n = 0; n < 2; ++n) _Pragma("unroll") for (int k = 0; k < 2; ++k) \
;     dst[n][k] = *(const LAS bf16x8*)((LAS char*)SB(b, h) + boff + n * 2048 + k * 1024)
; #define MMA(ai, bj, At_, Bt_) do { __builtin_amdgcn_s_setprio(1); \
;     _Pragma("unroll") for (int m = 0; m < 4; ++m) _Pragma("unroll") for (int n = 0; n < 2; ++n) _Pragma("unroll") for (int k = 0; k < 2; ++k) \
;       acc[ai][bj][m][n] = __builtin_amdgcn_mfma_f32_16x16x32_bf16(Bt_[n][k], At_[m][k], acc[ai][bj][m][n], 0, 0, 0); \
;     __builtin_amdgcn_s_setprio(0); } while (0)
; #define WAIT_L(n) asm volatile("s_waitcnt lgkmcnt(" #n ")" ::: "memory")
; #define BAR __builtin_amdgcn_s_barrier()
; #define SCHED __builtin_amdgcn_sched_barrier(0)
; __device__ __forceinline__ void gemm_phase(const bf16_t* __restrict__ A, const bf16_t* __restrict__ Bt, bf16_t* __restrict__ C, int M, int N, int K,
;                                            int ldc, const int EPI, char* smem, const int wid_u) {
;     ...
;       LDB(B0, 0, 0); SCHED; LDA(At, 0, 0); STG(SA(1, 1), a1 + hstep);
;       WAIT_L(8); BAR; WAIT_L(0); MMA(0, 0, At, B0); BAR; SCHED;
;       LDB(B1, 0, 1); STG(SB(0, 0), b2);
;       BAR; WAIT_L(0); MMA(0, 1, At, B1); BAR;
;       LDA(At, 0, 1); STG(SA(0, 0), a2);
;       BAR; WAIT_L(0); MMA(1, 0, At, B0); BAR; SCHED;
.LBB0_1026:
	ds_read_b128 v[150:153], v146
	ds_read_b128 v[154:157], v146 offset:1024
	ds_read_b128 v[158:161], v146 offset:2048
	ds_read_b128 v[162:165], v146 offset:3072
	s_add_u32 s20, s18, 0x100
	s_addc_u32 s21, s19, 0
	s_cmp_eq_u32 s53, 12
	s_cselect_b32 s25, s48, s21
	s_cselect_b32 s24, s49, s20
	s_cselect_b32 s23, s13, s52
	s_cselect_b32 s22, s50, s51
	v_lshl_add_u64 v[142:143], s[18:19], 0, v[136:137]
	s_add_i32 m0, s34, 0xc000
	ds_read_b128 v[166:169], v147
	ds_read_b128 v[170:173], v147 offset:1024
	ds_read_b128 v[174:177], v147 offset:2048
	ds_read_b128 v[178:181], v147 offset:3072
	ds_read_b128 v[182:185], v147 offset:4096
	ds_read_b128 v[186:189], v147 offset:5120
	ds_read_b128 v[190:193], v147 offset:6144
	ds_read_b128 v[194:197], v147 offset:7168
	global_load_lds_dwordx4 v[142:143], off
	v_lshl_add_u64 v[142:143], s[18:19], 0, v[134:135]
	s_add_i32 m0, s34, 0xe000
	s_nop 0
	global_load_lds_dwordx4 v[142:143], off
	s_waitcnt lgkmcnt(8)
	s_barrier
	s_waitcnt lgkmcnt(0)
	s_waitcnt lgkmcnt(0)
	v_mfma_f32_16x16x32_bf16 v[124:127], v[150:153], v[166:169], v[124:127]
	v_mfma_f32_16x16x32_bf16 v[120:123], v[158:161], v[166:169], v[120:123]
	v_mfma_f32_16x16x32_bf16 v[108:111], v[150:153], v[174:177], v[108:111]
	v_mfma_f32_16x16x32_bf16 v[104:107], v[158:161], v[174:177], v[104:107]
	v_mfma_f32_16x16x32_bf16 v[92:95], v[150:153], v[182:185], v[92:95]
	v_mfma_f32_16x16x32_bf16 v[88:91], v[158:161], v[182:185], v[88:91]
	v_mfma_f32_16x16x32_bf16 v[76:79], v[150:153], v[190:193], v[76:79]
	v_mfma_f32_16x16x32_bf16 v[72:75], v[158:161], v[190:193], v[72:75]
	v_mfma_f32_16x16x32_bf16 v[124:127], v[154:157], v[170:173], v[124:127]
	v_mfma_f32_16x16x32_bf16 v[120:123], v[162:165], v[170:173], v[120:123]
	v_mfma_f32_16x16x32_bf16 v[108:111], v[154:157], v[178:181], v[108:111]
	v_mfma_f32_16x16x32_bf16 v[104:107], v[162:165], v[178:181], v[104:107]
	v_mfma_f32_16x16x32_bf16 v[92:95], v[154:157], v[186:189], v[92:95]
	v_mfma_f32_16x16x32_bf16 v[88:91], v[162:165], v[186:189], v[88:91]
	v_mfma_f32_16x16x32_bf16 v[76:79], v[154:157], v[194:197], v[76:79]
	v_mfma_f32_16x16x32_bf16 v[72:75], v[162:165], v[194:197], v[72:75]
	s_barrier
	s_add_i32 s18, s40, s31
	v_lshl_add_u64 v[142:143], s[22:23], 0, v[130:131]
	s_mov_b32 m0, s18
	ds_read_b128 v[198:201], v148
	ds_read_b128 v[202:205], v148 offset:1024
	ds_read_b128 v[206:209], v148 offset:2048
	ds_read_b128 v[210:213], v148 offset:3072
	global_load_lds_dwordx4 v[142:143], off
	v_lshl_add_u64 v[214:215], s[22:23], 0, v[128:129]
	s_add_i32 m0, s18, 0x2000
	s_nop 0
	global_load_lds_dwordx4 v[214:215], off
	s_barrier
	s_waitcnt lgkmcnt(0)
	s_waitcnt lgkmcnt(0)
	v_mfma_f32_16x16x32_bf16 v[116:119], v[198:201], v[166:169], v[116:119]
	v_mfma_f32_16x16x32_bf16 v[112:115], v[206:209], v[166:169], v[112:115]
	v_mfma_f32_16x16x32_bf16 v[100:103], v[198:201], v[174:177], v[100:103]
	v_mfma_f32_16x16x32_bf16 v[96:99], v[206:209], v[174:177], v[96:99]
	v_mfma_f32_16x16x32_bf16 v[84:87], v[198:201], v[182:185], v[84:87]
	v_mfma_f32_16x16x32_bf16 v[80:83], v[206:209], v[182:185], v[80:83]
	v_mfma_f32_16x16x32_bf16 v[68:71], v[198:201], v[190:193], v[68:71]
	v_mfma_f32_16x16x32_bf16 v[64:67], v[206:209], v[190:193], v[64:67]
	v_mfma_f32_16x16x32_bf16 v[116:119], v[202:205], v[170:173], v[116:119]
	v_mfma_f32_16x16x32_bf16 v[112:115], v[210:213], v[170:173], v[112:115]
	v_mfma_f32_16x16x32_bf16 v[100:103], v[202:205], v[178:181], v[100:103]
	v_mfma_f32_16x16x32_bf16 v[96:99], v[210:213], v[178:181], v[96:99]
	v_mfma_f32_16x16x32_bf16 v[84:87], v[202:205], v[186:189], v[84:87]
	v_mfma_f32_16x16x32_bf16 v[80:83], v[210:213], v[186:189], v[80:83]
	v_mfma_f32_16x16x32_bf16 v[68:71], v[202:205], v[194:197], v[68:71]
	v_mfma_f32_16x16x32_bf16 v[64:67], v[210:213], v[194:197], v[64:67]
	s_mov_b32 m0, s34
	v_lshl_add_u64 v[216:217], s[24:25], 0, v[130:131]
	s_barrier
	ds_read_b128 v[166:169], v147 offset:16384
	ds_read_b128 v[170:173], v147 offset:17408
	ds_read_b128 v[174:177], v147 offset:18432
	ds_read_b128 v[178:181], v147 offset:19456
	ds_read_b128 v[182:185], v147 offset:20480
	ds_read_b128 v[186:189], v147 offset:21504
	ds_read_b128 v[190:193], v147 offset:22528
	ds_read_b128 v[194:197], v147 offset:23552
	global_load_lds_dwordx4 v[216:217], off
	v_lshl_add_u64 v[218:219], s[24:25], 0, v[128:129]
	s_mov_b32 m0, s35
	s_nop 0
	global_load_lds_dwordx4 v[218:219], off
	s_barrier
	s_waitcnt lgkmcnt(0)
	s_waitcnt lgkmcnt(0)
	v_mfma_f32_16x16x32_bf16 v[60:63], v[150:153], v[166:169], v[60:63]
	v_mfma_f32_16x16x32_bf16 v[56:59], v[158:161], v[166:169], v[56:59]
	v_mfma_f32_16x16x32_bf16 v[44:47], v[150:153], v[174:177], v[44:47]
	v_mfma_f32_16x16x32_bf16 v[40:43], v[158:161], v[174:177], v[40:43]
	v_mfma_f32_16x16x32_bf16 v[28:31], v[150:153], v[182:185], v[28:31]
	v_mfma_f32_16x16x32_bf16 v[24:27], v[158:161], v[182:185], v[24:27]
	v_mfma_f32_16x16x32_bf16 v[12:15], v[150:153], v[190:193], v[12:15]
	v_mfma_f32_16x16x32_bf16 v[8:11], v[158:161], v[190:193], v[8:11]
	v_mfma_f32_16x16x32_bf16 v[60:63], v[154:157], v[170:173], v[60:63]
	v_mfma_f32_16x16x32_bf16 v[56:59], v[162:165], v[170:173], v[56:59]
	v_mfma_f32_16x16x32_bf16 v[44:47], v[154:157], v[178:181], v[44:47]
	v_mfma_f32_16x16x32_bf16 v[40:43], v[162:165], v[178:181], v[40:43]
	v_mfma_f32_16x16x32_bf16 v[28:31], v[154:157], v[186:189], v[28:31]
	v_mfma_f32_16x16x32_bf16 v[24:27], v[162:165], v[186:189], v[24:27]
	v_mfma_f32_16x16x32_bf16 v[12:15], v[154:157], v[194:197], v[12:15]
	v_mfma_f32_16x16x32_bf16 v[8:11], v[162:165], v[194:197], v[8:11]
	s_barrier
; #define STG(P, GB) do { const char* _gb = (GB); \
;     _Pragma("unroll") for (int _i = 0; _i < 2; ++_i) { \
;       __builtin_amdgcn_global_load_lds((const unsigned*)(_gb + voff[_i]), \
;         (LAS unsigned*)((LAS char*)(P) + ldsw + _i * 8192), 16, 0, 0); } } while (0)
; #define LDA(dst, b, h) _Pragma("unroll") for (int m = 0; m < 4; ++m) _Pragma("unroll") for (int k = 0; k < 2; ++k) \
;     dst[m][k] = *(const LAS bf16x8*)((LAS char*)SA(b, h) + aoff + m * 2048 + k * 1024)
; #define LDB(dst, b, h) _Pragma("unroll") for (int n = 0; n < 2; ++n) _Pragma("unroll") for (int k = 0; k < 2; ++k) \
;     dst[n][k] = *(const LAS bf16x8*)((LAS char*)SB(b, h) + boff + n * 2048 + k * 1024)
; #define MMA(ai, bj, At_, Bt_) do { __builtin_amdgcn_s_setprio(1); \
;     _Pragma("unroll") for (int m = 0; m < 4; ++m) _Pragma("unroll") for (int n = 0; n < 2; ++n) _Pragma("unroll") for (int k = 0; k < 2; ++k) \
;       acc[ai][bj][m][n] = __builtin_amdgcn_mfma_f32_16x16x32_bf16(Bt_[n][k], At_[m][k], acc[ai][bj][m][n], 0, 0, 0); \
;     __builtin_amdgcn_s_setprio(0); } while (0)
; #define WAIT_V(n) asm volatile("s_waitcnt vmcnt(" #n ")" ::: "memory")
; #define WAIT_L(n) asm volatile("s_waitcnt lgkmcnt(" #n ")" ::: "memory")
; #define BAR __builtin_amdgcn_s_barrier()
; #define SCHED __builtin_amdgcn_sched_barrier(0)
; __device__ __forceinline__ void gemm_phase(const bf16_t* __restrict__ A, const bf16_t* __restrict__ Bt, bf16_t* __restrict__ C, int M, int N, int K,
;                                            int ldc, const int EPI, char* smem, const int wid_u) {
;     ...
;       STG(SB(0, 1), b2 + hstep);
;       WAIT_V(6); BAR; MMA(1, 1, At, B1); BAR;
;       LDB(B0, 1, 0); SCHED; LDA(At, 1, 0); STG(SA(0, 1), a2 + hstep);
;       WAIT_L(8); BAR; WAIT_L(0); MMA(0, 0, At, B0); BAR; SCHED;
;       LDB(B1, 1, 1); STG(SB(1, 0), b3);
;       BAR; WAIT_L(0); MMA(0, 1, At, B1); BAR;
;       LDA(At, 1, 1); STG(SA(1, 0), a3);
;       BAR; WAIT_L(0); MMA(1, 0, At, B0); BAR; SCHED;
	s_add_u32 s18, s22, 0x40000
	s_addc_u32 s19, s23, 0
	s_add_i32 s54, s41, s31
	v_lshl_add_u64 v[150:151], s[18:19], 0, v[130:131]
	s_mov_b32 m0, s54
	s_nop 0
	global_load_lds_dwordx4 v[150:151], off
	v_lshl_add_u64 v[150:151], s[18:19], 0, v[128:129]
	s_add_i32 m0, s54, 0x2000
	s_nop 0
	global_load_lds_dwordx4 v[150:151], off
	s_waitcnt vmcnt(6)
	s_barrier
	v_mfma_f32_16x16x32_bf16 v[52:55], v[198:201], v[166:169], v[52:55]
	v_mfma_f32_16x16x32_bf16 v[48:51], v[206:209], v[166:169], v[48:51]
	v_mfma_f32_16x16x32_bf16 v[36:39], v[198:201], v[174:177], v[36:39]
	v_mfma_f32_16x16x32_bf16 v[32:35], v[206:209], v[174:177], v[32:35]
	v_mfma_f32_16x16x32_bf16 v[20:23], v[198:201], v[182:185], v[20:23]
	v_mfma_f32_16x16x32_bf16 v[16:19], v[206:209], v[182:185], v[16:19]
	v_mfma_f32_16x16x32_bf16 v[4:7], v[198:201], v[190:193], v[4:7]
	v_mfma_f32_16x16x32_bf16 v[0:3], v[206:209], v[190:193], v[0:3]
	v_mfma_f32_16x16x32_bf16 v[52:55], v[202:205], v[170:173], v[52:55]
	v_mfma_f32_16x16x32_bf16 v[48:51], v[210:213], v[170:173], v[48:51]
	v_mfma_f32_16x16x32_bf16 v[36:39], v[202:205], v[178:181], v[36:39]
	v_mfma_f32_16x16x32_bf16 v[32:35], v[210:213], v[178:181], v[32:35]
	v_mfma_f32_16x16x32_bf16 v[20:23], v[202:205], v[186:189], v[20:23]
	v_mfma_f32_16x16x32_bf16 v[16:19], v[210:213], v[186:189], v[16:19]
	v_mfma_f32_16x16x32_bf16 v[4:7], v[202:205], v[194:197], v[4:7]
	v_mfma_f32_16x16x32_bf16 v[0:3], v[210:213], v[194:197], v[0:3]
	s_add_i32 s54, 0, 0x18000
	v_add_u32_e32 v149, s54, v145
	s_barrier
	ds_read_b128 v[150:153], v149
	ds_read_b128 v[154:157], v149 offset:1024
	ds_read_b128 v[158:161], v149 offset:2048
	ds_read_b128 v[162:165], v149 offset:3072
	s_add_u32 s18, s24, 0x40000
	s_addc_u32 s19, s25, 0
	s_mov_b32 m0, s36
	v_lshl_add_u64 v[198:199], s[18:19], 0, v[130:131]
	ds_read_b128 v[166:169], v147 offset:32768
	ds_read_b128 v[170:173], v147 offset:33792
	ds_read_b128 v[174:177], v147 offset:34816
	ds_read_b128 v[178:181], v147 offset:35840
	ds_read_b128 v[182:185], v147 offset:36864
	ds_read_b128 v[186:189], v147 offset:37888
	ds_read_b128 v[190:193], v147 offset:38912
	ds_read_b128 v[194:197], v147 offset:39936
	global_load_lds_dwordx4 v[198:199], off
	v_lshl_add_u64 v[198:199], s[18:19], 0, v[128:129]
	s_mov_b32 m0, s37
	s_nop 0
	global_load_lds_dwordx4 v[198:199], off
	s_waitcnt lgkmcnt(8)
	s_barrier
	s_waitcnt lgkmcnt(0)
	s_waitcnt lgkmcnt(0)
	v_mfma_f32_16x16x32_bf16 v[124:127], v[150:153], v[166:169], v[124:127]
	v_mfma_f32_16x16x32_bf16 v[120:123], v[158:161], v[166:169], v[120:123]
	v_mfma_f32_16x16x32_bf16 v[108:111], v[150:153], v[174:177], v[108:111]
	v_mfma_f32_16x16x32_bf16 v[104:107], v[158:161], v[174:177], v[104:107]
	v_mfma_f32_16x16x32_bf16 v[92:95], v[150:153], v[182:185], v[92:95]
	v_mfma_f32_16x16x32_bf16 v[88:91], v[158:161], v[182:185], v[88:91]
	v_mfma_f32_16x16x32_bf16 v[76:79], v[150:153], v[190:193], v[76:79]
	v_mfma_f32_16x16x32_bf16 v[72:75], v[158:161], v[190:193], v[72:75]
	v_mfma_f32_16x16x32_bf16 v[124:127], v[154:157], v[170:173], v[124:127]
	v_mfma_f32_16x16x32_bf16 v[120:123], v[162:165], v[170:173], v[120:123]
	v_mfma_f32_16x16x32_bf16 v[108:111], v[154:157], v[178:181], v[108:111]
	v_mfma_f32_16x16x32_bf16 v[104:107], v[162:165], v[178:181], v[104:107]
	v_mfma_f32_16x16x32_bf16 v[92:95], v[154:157], v[186:189], v[92:95]
	v_mfma_f32_16x16x32_bf16 v[88:91], v[162:165], v[186:189], v[88:91]
	v_mfma_f32_16x16x32_bf16 v[76:79], v[154:157], v[194:197], v[76:79]
	v_mfma_f32_16x16x32_bf16 v[72:75], v[162:165], v[194:197], v[72:75]
	s_barrier
	s_add_i32 s24, 0, 0x1c000
	s_add_i32 s18, s54, s31
	v_add_u32_e32 v149, s24, v145
	v_lshl_add_u64 v[142:143], v[142:143], 0, s[10:11]
	s_mov_b32 m0, s18
	ds_read_b128 v[198:201], v149
	ds_read_b128 v[202:205], v149 offset:1024
	ds_read_b128 v[206:209], v149 offset:2048
	ds_read_b128 v[210:213], v149 offset:3072
	global_load_lds_dwordx4 v[142:143], off
	v_lshl_add_u64 v[142:143], v[214:215], 0, s[10:11]
	s_add_i32 m0, s18, 0x2000
	s_nop 0
	global_load_lds_dwordx4 v[142:143], off
	s_barrier
	s_waitcnt lgkmcnt(0)
	s_waitcnt lgkmcnt(0)
	v_mfma_f32_16x16x32_bf16 v[116:119], v[198:201], v[166:169], v[116:119]
	v_mfma_f32_16x16x32_bf16 v[112:115], v[206:209], v[166:169], v[112:115]
	v_mfma_f32_16x16x32_bf16 v[100:103], v[198:201], v[174:177], v[100:103]
	v_mfma_f32_16x16x32_bf16 v[96:99], v[206:209], v[174:177], v[96:99]
	v_mfma_f32_16x16x32_bf16 v[84:87], v[198:201], v[182:185], v[84:87]
	v_mfma_f32_16x16x32_bf16 v[80:83], v[206:209], v[182:185], v[80:83]
	v_mfma_f32_16x16x32_bf16 v[68:71], v[198:201], v[190:193], v[68:71]
	v_mfma_f32_16x16x32_bf16 v[64:67], v[206:209], v[190:193], v[64:67]
	v_mfma_f32_16x16x32_bf16 v[116:119], v[202:205], v[170:173], v[116:119]
	v_mfma_f32_16x16x32_bf16 v[112:115], v[210:213], v[170:173], v[112:115]
	v_mfma_f32_16x16x32_bf16 v[100:103], v[202:205], v[178:181], v[100:103]
	v_mfma_f32_16x16x32_bf16 v[96:99], v[210:213], v[178:181], v[96:99]
	v_mfma_f32_16x16x32_bf16 v[84:87], v[202:205], v[186:189], v[84:87]
	v_mfma_f32_16x16x32_bf16 v[80:83], v[210:213], v[186:189], v[80:83]
	v_mfma_f32_16x16x32_bf16 v[68:71], v[202:205], v[194:197], v[68:71]
	v_mfma_f32_16x16x32_bf16 v[64:67], v[210:213], v[194:197], v[64:67]
	s_mov_b32 m0, s38
	v_lshl_add_u64 v[142:143], v[216:217], 0, s[10:11]
	s_barrier
	ds_read_b128 v[166:169], v147 offset:49152
	ds_read_b128 v[170:173], v147 offset:50176
	ds_read_b128 v[174:177], v147 offset:51200
	ds_read_b128 v[178:181], v147 offset:52224
	ds_read_b128 v[182:185], v147 offset:53248
	ds_read_b128 v[186:189], v147 offset:54272
	ds_read_b128 v[190:193], v147 offset:55296
	ds_read_b128 v[194:197], v147 offset:56320
	global_load_lds_dwordx4 v[142:143], off
	v_lshl_add_u64 v[142:143], v[218:219], 0, s[10:11]
	s_mov_b32 m0, s39
	s_nop 0
	global_load_lds_dwordx4 v[142:143], off
	s_barrier
; #define STG(P, GB) do { const char* _gb = (GB); \
;     _Pragma("unroll") for (int _i = 0; _i < 2; ++_i) { \
;       __builtin_amdgcn_global_load_lds((const unsigned*)(_gb + voff[_i]), \
;         (LAS unsigned*)((LAS char*)(P) + ldsw + _i * 8192), 16, 0, 0); } } while (0)
; #define MMA(ai, bj, At_, Bt_) do { __builtin_amdgcn_s_setprio(1); \
;     _Pragma("unroll") for (int m = 0; m < 4; ++m) _Pragma("unroll") for (int n = 0; n < 2; ++n) _Pragma("unroll") for (int k = 0; k < 2; ++k) \
;       acc[ai][bj][m][n] = __builtin_amdgcn_mfma_f32_16x16x32_bf16(Bt_[n][k], At_[m][k], acc[ai][bj][m][n], 0, 0, 0); \
;     __builtin_amdgcn_s_setprio(0); } while (0)
; #define WAIT_V(n) asm volatile("s_waitcnt vmcnt(" #n ")" ::: "memory")
; #define BAR __builtin_amdgcn_s_barrier()
; __device__ __forceinline__ void gemm_phase(const bf16_t* __restrict__ A, const bf16_t* __restrict__ Bt, bf16_t* __restrict__ C, int M, int N, int K,
;                                            int ldc, const int EPI, char* smem, const int wid_u) {
;     ...
;       STG(SB(1, 1), b3 + hstep);
;       WAIT_V(6); BAR; MMA(1, 1, At, B1); BAR;
;     ...
;             float o[8];
; #pragma unroll
;             for (int n = 0; n < 2; ++n) {
;               const f32x4 a = acc[ai][0][m][n], b = acc[ai][1][m][n];
; #pragma unroll
;               for (int j = 0; j < 4; ++j) o[n * 4 + j] = a[j] * __builtin_amdgcn_rcpf(1.f + __expf(-a[j])) * b[j];
;             }
;             *(uint4*)(C + row * ldc + (bcol >> 1) + wc * 32 + fq * 8) = pack8(o);
	s_waitcnt lgkmcnt(0)
	s_waitcnt lgkmcnt(0)
	v_mfma_f32_16x16x32_bf16 v[60:63], v[150:153], v[166:169], v[60:63]
	v_mfma_f32_16x16x32_bf16 v[56:59], v[158:161], v[166:169], v[56:59]
	v_mfma_f32_16x16x32_bf16 v[44:47], v[150:153], v[174:177], v[44:47]
	v_mfma_f32_16x16x32_bf16 v[40:43], v[158:161], v[174:177], v[40:43]
	v_mfma_f32_16x16x32_bf16 v[28:31], v[150:153], v[182:185], v[28:31]
	v_mfma_f32_16x16x32_bf16 v[24:27], v[158:161], v[182:185], v[24:27]
	v_mfma_f32_16x16x32_bf16 v[12:15], v[150:153], v[190:193], v[12:15]
	v_mfma_f32_16x16x32_bf16 v[8:11], v[158:161], v[190:193], v[8:11]
	v_mfma_f32_16x16x32_bf16 v[60:63], v[154:157], v[170:173], v[60:63]
	v_mfma_f32_16x16x32_bf16 v[56:59], v[162:165], v[170:173], v[56:59]
	v_mfma_f32_16x16x32_bf16 v[44:47], v[154:157], v[178:181], v[44:47]
	v_mfma_f32_16x16x32_bf16 v[40:43], v[162:165], v[178:181], v[40:43]
	v_mfma_f32_16x16x32_bf16 v[28:31], v[154:157], v[186:189], v[28:31]
	v_mfma_f32_16x16x32_bf16 v[24:27], v[162:165], v[186:189], v[24:27]
	v_mfma_f32_16x16x32_bf16 v[12:15], v[154:157], v[194:197], v[12:15]
	v_mfma_f32_16x16x32_bf16 v[8:11], v[162:165], v[194:197], v[8:11]
	s_barrier
	s_add_u32 s18, s22, 0x40080
	s_addc_u32 s19, s23, 0
	s_add_i32 s22, s24, s31
	v_lshl_add_u64 v[142:143], s[18:19], 0, v[130:131]
	s_mov_b32 m0, s22
	s_nop 0
	global_load_lds_dwordx4 v[142:143], off
	v_lshl_add_u64 v[142:143], s[18:19], 0, v[128:129]
	s_add_i32 m0, s22, 0x2000
	s_nop 0
	global_load_lds_dwordx4 v[142:143], off
	s_waitcnt vmcnt(6)
	s_barrier
	v_mfma_f32_16x16x32_bf16 v[52:55], v[198:201], v[166:169], v[52:55]
	v_mfma_f32_16x16x32_bf16 v[48:51], v[206:209], v[166:169], v[48:51]
	v_mfma_f32_16x16x32_bf16 v[36:39], v[198:201], v[174:177], v[36:39]
	v_mfma_f32_16x16x32_bf16 v[32:35], v[206:209], v[174:177], v[32:35]
	v_mfma_f32_16x16x32_bf16 v[20:23], v[198:201], v[182:185], v[20:23]
	v_mfma_f32_16x16x32_bf16 v[16:19], v[206:209], v[182:185], v[16:19]
	v_mfma_f32_16x16x32_bf16 v[4:7], v[198:201], v[190:193], v[4:7]
	v_mfma_f32_16x16x32_bf16 v[0:3], v[206:209], v[190:193], v[0:3]
	v_mfma_f32_16x16x32_bf16 v[52:55], v[202:205], v[170:173], v[52:55]
	v_mfma_f32_16x16x32_bf16 v[48:51], v[210:213], v[170:173], v[48:51]
	v_mfma_f32_16x16x32_bf16 v[36:39], v[202:205], v[178:181], v[36:39]
	v_mfma_f32_16x16x32_bf16 v[32:35], v[210:213], v[178:181], v[32:35]
	v_mfma_f32_16x16x32_bf16 v[20:23], v[202:205], v[186:189], v[20:23]
	v_mfma_f32_16x16x32_bf16 v[16:19], v[210:213], v[186:189], v[16:19]
	v_mfma_f32_16x16x32_bf16 v[4:7], v[202:205], v[194:197], v[4:7]
	v_mfma_f32_16x16x32_bf16 v[0:3], v[210:213], v[194:197], v[0:3]
	s_add_i32 s53, s53, 2
	s_add_u32 s51, s51, 0x100
	s_addc_u32 s52, s52, 0
	s_cmp_gt_u32 s53, 13
	s_mov_b64 s[18:19], s[20:21]
	s_barrier
	s_cbranch_scc0 .LBB0_1026
	v_mul_f32_e32 v142, 0xbfb8aa3b, v124
	v_exp_f32_e32 v142, v142
	v_mul_f32_e32 v143, 0xbfb8aa3b, v125
	v_exp_f32_e32 v143, v143
	s_lshl_b32 s18, s46, 8
	v_add_f32_e32 v142, 1.0, v142
	v_rcp_f32_e32 v150, v142
	v_add_f32_e32 v142, 1.0, v143
	v_rcp_f32_e32 v151, v142
	s_mov_b32 s19, s9
	v_lshl_add_u32 v149, s47, 8, v144
	v_lshl_add_u64 v[142:143], v[132:133], 0, s[18:19]
	v_mul_f32_e64 v124, v124, v150
	v_mul_f32_e64 v125, v125, v151
	v_mul_f32_e32 v150, 0xbfb8aa3b, v126
	v_mul_f32_e32 v151, 0xbfb8aa3b, v127
	v_exp_f32_e32 v150, v150
	v_exp_f32_e32 v151, v151
	v_mul_f32_e64 v116, v124, v116
	v_mul_f32_e64 v117, v125, v117
	s_and_b64 vcc, exec, s[4:5]
	v_add_f32_e32 v124, 1.0, v150
	v_add_f32_e32 v125, 1.0, v151
	v_mul_f32_e32 v150, 0xbfb8aa3b, v120
	v_mul_f32_e32 v151, 0xbfb8aa3b, v121
	v_rcp_f32_e32 v124, v124
	v_rcp_f32_e32 v125, v125
	v_exp_f32_e32 v150, v150
	v_exp_f32_e32 v151, v151
	s_mov_b32 s47, s8
	v_mul_f32_e64 v124, v126, v124
	v_mul_f32_e64 v125, v127, v125
	v_add_f32_e32 v126, 1.0, v150
	v_add_f32_e32 v127, 1.0, v151
	v_mul_f32_e32 v150, 0xbfb8aa3b, v122
	v_mul_f32_e32 v151, 0xbfb8aa3b, v123
	v_exp_f32_e32 v150, v150
	v_exp_f32_e32 v151, v151
	v_rcp_f32_e32 v126, v126
	v_rcp_f32_e32 v127, v127
	v_add_f32_e32 v150, 1.0, v150
	v_add_f32_e32 v151, 1.0, v151
	v_rcp_f32_e32 v150, v150
	v_rcp_f32_e32 v151, v151
	v_mul_f32_e64 v120, v120, v126
	v_mul_f32_e64 v121, v121, v127
	v_mul_f32_e64 v118, v124, v118
	v_mul_f32_e64 v119, v125, v119
	v_mul_f32_e64 v120, v120, v112
	v_mul_f32_e64 v121, v121, v113
	v_mul_f32_e64 v112, v122, v150
	v_mul_f32_e64 v113, v123, v151
	s_mov_b32 s46, s12
	v_mul_f32_e64 v122, v112, v114
	v_mul_f32_e64 v123, v113, v115
	v_mul_f32_e32 v115, 0xbfb8aa3b, v108
	v_cvt_pk_bf16_f32 v112, v116, v117
	v_exp_f32_e32 v116, v115
	v_mul_f32_e32 v115, 0xbfb8aa3b, v109
	v_exp_f32_e32 v117, v115
	v_cvt_pk_bf16_f32 v113, v118, v119
	v_cvt_pk_bf16_f32 v114, v120, v121
	v_cvt_pk_bf16_f32 v115, v122, v123
	v_add_f32_e32 v116, 1.0, v116
	v_add_f32_e32 v117, 1.0, v117
	v_mad_i64_i32 v[118:119], s[18:19], v149, s44, v[142:143]
	v_rcp_f32_e32 v116, v116
	v_rcp_f32_e32 v117, v117
	global_store_dwordx4 v[118:119], v[112:115], off
	s_mov_b64 s[20:21], s[16:17]
	v_mul_f32_e64 v108, v108, v116
	v_mul_f32_e64 v109, v109, v117
	v_mul_f32_e32 v112, 0xbfb8aa3b, v110
	v_mul_f32_e32 v113, 0xbfb8aa3b, v111
	v_exp_f32_e32 v112, v112
	v_exp_f32_e32 v113, v113
	v_mul_f32_e64 v100, v108, v100
	v_mul_f32_e64 v101, v109, v101
	v_or_b32_e32 v114, 16, v149
	v_add_f32_e32 v108, 1.0, v112
	v_add_f32_e32 v109, 1.0, v113
	v_mul_f32_e32 v112, 0xbfb8aa3b, v104
	v_mul_f32_e32 v113, 0xbfb8aa3b, v105
	v_rcp_f32_e32 v108, v108
	v_rcp_f32_e32 v109, v109
	v_exp_f32_e32 v112, v112
	v_exp_f32_e32 v113, v113
	v_mul_f32_e64 v108, v110, v108
	v_mul_f32_e64 v109, v111, v109
	v_add_f32_e32 v110, 1.0, v112
	v_add_f32_e32 v111, 1.0, v113
; __device__ __forceinline__ void gemm_phase(const bf16_t* __restrict__ A, const bf16_t* __restrict__ Bt, bf16_t* __restrict__ C, int M, int N, int K,
;                                            int ldc, const int EPI, char* smem, const int wid_u) {
;     ...
;             float o[8];
; #pragma unroll
;             for (int n = 0; n < 2; ++n) {
;               const f32x4 a = acc[ai][0][m][n], b = acc[ai][1][m][n];
; #pragma unroll
;               for (int j = 0; j < 4; ++j) o[n * 4 + j] = a[j] * __builtin_amdgcn_rcpf(1.f + __expf(-a[j])) * b[j];
;             }
;             *(uint4*)(C + row * ldc + (bcol >> 1) + wc * 32 + fq * 8) = pack8(o);
	v_mul_f32_e32 v112, 0xbfb8aa3b, v106
	v_mul_f32_e32 v113, 0xbfb8aa3b, v107
	v_exp_f32_e32 v112, v112
	v_exp_f32_e32 v113, v113
	v_rcp_f32_e32 v110, v110
	v_rcp_f32_e32 v111, v111
	v_add_f32_e32 v112, 1.0, v112
	v_add_f32_e32 v113, 1.0, v113
	v_rcp_f32_e32 v112, v112
	v_rcp_f32_e32 v113, v113
	v_mul_f32_e64 v104, v104, v110
	v_mul_f32_e64 v105, v105, v111
	v_mul_f32_e64 v102, v108, v102
	v_mul_f32_e64 v103, v109, v103
	v_mul_f32_e64 v104, v104, v96
	v_mul_f32_e64 v105, v105, v97
	v_mul_f32_e64 v96, v106, v112
	v_mul_f32_e64 v97, v107, v113
	s_nop 0
	v_mul_f32_e64 v106, v96, v98
	v_mul_f32_e64 v107, v97, v99
	v_mul_f32_e32 v99, 0xbfb8aa3b, v92
	v_cvt_pk_bf16_f32 v96, v100, v101
	v_exp_f32_e32 v100, v99
	v_mul_f32_e32 v99, 0xbfb8aa3b, v93
	v_exp_f32_e32 v101, v99
	v_cvt_pk_bf16_f32 v97, v102, v103
	v_cvt_pk_bf16_f32 v98, v104, v105
	v_cvt_pk_bf16_f32 v99, v106, v107
	v_add_f32_e32 v100, 1.0, v100
	v_add_f32_e32 v101, 1.0, v101
	v_mad_i64_i32 v[102:103], s[18:19], v114, s44, v[142:143]
	v_rcp_f32_e32 v100, v100
	v_rcp_f32_e32 v101, v101
	global_store_dwordx4 v[102:103], v[96:99], off
	v_mul_f32_e64 v92, v92, v100
	v_mul_f32_e64 v93, v93, v101
	s_nop 0
	v_mul_f32_e32 v96, 0xbfb8aa3b, v94
	v_mul_f32_e32 v97, 0xbfb8aa3b, v95
	v_exp_f32_e32 v96, v96
	v_exp_f32_e32 v97, v97
	v_mul_f32_e64 v84, v92, v84
	v_mul_f32_e64 v85, v93, v85
	v_or_b32_e32 v98, 32, v149
	v_add_f32_e32 v92, 1.0, v96
	v_add_f32_e32 v93, 1.0, v97
	v_mul_f32_e32 v96, 0xbfb8aa3b, v88
	v_mul_f32_e32 v97, 0xbfb8aa3b, v89
	v_rcp_f32_e32 v92, v92
	v_rcp_f32_e32 v93, v93
	v_exp_f32_e32 v96, v96
	v_exp_f32_e32 v97, v97
	v_mul_f32_e64 v92, v94, v92
	v_mul_f32_e64 v93, v95, v93
	v_add_f32_e32 v94, 1.0, v96
	v_add_f32_e32 v95, 1.0, v97
	v_mul_f32_e32 v96, 0xbfb8aa3b, v90
	v_mul_f32_e32 v97, 0xbfb8aa3b, v91
	v_exp_f32_e32 v96, v96
	v_exp_f32_e32 v97, v97
	v_rcp_f32_e32 v94, v94
	v_rcp_f32_e32 v95, v95
	v_add_f32_e32 v96, 1.0, v96
	v_add_f32_e32 v97, 1.0, v97
	v_rcp_f32_e32 v96, v96
	v_rcp_f32_e32 v97, v97
	v_mul_f32_e64 v88, v88, v94
	v_mul_f32_e64 v89, v89, v95
	v_mul_f32_e64 v86, v92, v86
	v_mul_f32_e64 v87, v93, v87
	v_mul_f32_e64 v88, v88, v80
	v_mul_f32_e64 v89, v89, v81
	v_mul_f32_e64 v80, v90, v96
	v_mul_f32_e64 v81, v91, v97
	s_nop 0
	v_mul_f32_e64 v90, v80, v82
	v_mul_f32_e64 v91, v81, v83
	v_mul_f32_e32 v83, 0xbfb8aa3b, v76
	v_cvt_pk_bf16_f32 v80, v84, v85
	v_exp_f32_e32 v84, v83
	v_mul_f32_e32 v83, 0xbfb8aa3b, v77
	v_exp_f32_e32 v85, v83
	v_cvt_pk_bf16_f32 v81, v86, v87
	v_cvt_pk_bf16_f32 v82, v88, v89
	v_cvt_pk_bf16_f32 v83, v90, v91
	v_add_f32_e32 v84, 1.0, v84
	v_add_f32_e32 v85, 1.0, v85
	v_mad_i64_i32 v[86:87], s[18:19], v98, s44, v[142:143]
	v_rcp_f32_e32 v84, v84
	v_rcp_f32_e32 v85, v85
	global_store_dwordx4 v[86:87], v[80:83], off
	v_mul_f32_e64 v76, v76, v84
	v_mul_f32_e64 v77, v77, v85
	s_nop 0
	v_mul_f32_e32 v80, 0xbfb8aa3b, v78
	v_mul_f32_e32 v81, 0xbfb8aa3b, v79
	v_exp_f32_e32 v80, v80
	v_exp_f32_e32 v81, v81
	v_mul_f32_e64 v68, v76, v68
	v_mul_f32_e64 v69, v77, v69
	v_or_b32_e32 v82, 48, v149
	v_add_f32_e32 v76, 1.0, v80
	v_add_f32_e32 v77, 1.0, v81
	v_mul_f32_e32 v80, 0xbfb8aa3b, v72
	v_mul_f32_e32 v81, 0xbfb8aa3b, v73
	v_rcp_f32_e32 v76, v76
	v_rcp_f32_e32 v77, v77
	v_exp_f32_e32 v80, v80
	v_exp_f32_e32 v81, v81
	v_mul_f32_e64 v76, v78, v76
	v_mul_f32_e64 v77, v79, v77
	v_add_f32_e32 v78, 1.0, v80
	v_add_f32_e32 v79, 1.0, v81
	v_mul_f32_e32 v80, 0xbfb8aa3b, v74
	v_mul_f32_e32 v81, 0xbfb8aa3b, v75
	v_exp_f32_e32 v80, v80
	v_exp_f32_e32 v81, v81
	v_rcp_f32_e32 v78, v78
	v_rcp_f32_e32 v79, v79
	v_add_f32_e32 v80, 1.0, v80
	v_add_f32_e32 v81, 1.0, v81
	v_rcp_f32_e32 v80, v80
	v_rcp_f32_e32 v81, v81
	v_mul_f32_e64 v72, v72, v78
	v_mul_f32_e64 v73, v73, v79
	v_mul_f32_e64 v70, v76, v70
	v_mul_f32_e64 v71, v77, v71
	v_mul_f32_e64 v72, v72, v64
	v_mul_f32_e64 v73, v73, v65
	v_mul_f32_e64 v64, v74, v80
	v_mul_f32_e64 v65, v75, v81
	s_nop 0
	v_mul_f32_e64 v74, v64, v66
	v_mul_f32_e64 v75, v65, v67
	v_mul_f32_e32 v67, 0xbfb8aa3b, v60
	v_cvt_pk_bf16_f32 v64, v68, v69
	v_exp_f32_e32 v68, v67
	v_mul_f32_e32 v67, 0xbfb8aa3b, v61
	v_exp_f32_e32 v69, v67
	v_cvt_pk_bf16_f32 v65, v70, v71
	v_cvt_pk_bf16_f32 v66, v72, v73
	v_cvt_pk_bf16_f32 v67, v74, v75
	v_add_f32_e32 v68, 1.0, v68
	v_add_f32_e32 v69, 1.0, v69
	v_mad_i64_i32 v[70:71], s[18:19], v82, s44, v[142:143]
	v_rcp_f32_e32 v68, v68
	v_rcp_f32_e32 v69, v69
	global_store_dwordx4 v[70:71], v[64:67], off
	v_mul_f32_e64 v60, v60, v68
	v_mul_f32_e64 v61, v61, v69
	s_nop 0
	v_mul_f32_e32 v64, 0xbfb8aa3b, v62
	v_mul_f32_e32 v65, 0xbfb8aa3b, v63
	v_exp_f32_e32 v64, v64
	v_exp_f32_e32 v65, v65
	v_mul_f32_e64 v52, v60, v52
	v_mul_f32_e64 v53, v61, v53
	v_add_u32_e32 v66, 0x80, v149
	v_add_f32_e32 v60, 1.0, v64
	v_add_f32_e32 v61, 1.0, v65
	v_mul_f32_e32 v64, 0xbfb8aa3b, v56
	v_mul_f32_e32 v65, 0xbfb8aa3b, v57
	v_rcp_f32_e32 v60, v60
	v_rcp_f32_e32 v61, v61
	v_exp_f32_e32 v64, v64
	v_exp_f32_e32 v65, v65
	v_mul_f32_e64 v60, v62, v60
	v_mul_f32_e64 v61, v63, v61
	v_add_f32_e32 v62, 1.0, v64
	v_add_f32_e32 v63, 1.0, v65
	v_mul_f32_e32 v64, 0xbfb8aa3b, v58
	v_mul_f32_e32 v65, 0xbfb8aa3b, v59
	v_exp_f32_e32 v64, v64
	v_exp_f32_e32 v65, v65
	v_rcp_f32_e32 v62, v62
	v_rcp_f32_e32 v63, v63
	v_add_f32_e32 v64, 1.0, v64
	v_add_f32_e32 v65, 1.0, v65
	v_rcp_f32_e32 v64, v64
	v_rcp_f32_e32 v65, v65
	v_mul_f32_e64 v56, v56, v62
	v_mul_f32_e64 v57, v57, v63
	v_mul_f32_e64 v54, v60, v54
	v_mul_f32_e64 v55, v61, v55
	v_mul_f32_e64 v56, v56, v48
; #define WAIT_V(n) asm volatile("s_waitcnt vmcnt(" #n ")" ::: "memory")
; #define BAR __builtin_amdgcn_s_barrier()
; __device__ __forceinline__ void gemm_phase(const bf16_t* __restrict__ A, const bf16_t* __restrict__ Bt, bf16_t* __restrict__ C, int M, int N, int K,
;                                            int ldc, const int EPI, char* smem, const int wid_u) {
;     ...
;             float o[8];
; #pragma unroll
;             for (int n = 0; n < 2; ++n) {
;               const f32x4 a = acc[ai][0][m][n], b = acc[ai][1][m][n];
; #pragma unroll
;               for (int j = 0; j < 4; ++j) o[n * 4 + j] = a[j] * __builtin_amdgcn_rcpf(1.f + __expf(-a[j])) * b[j];
;             }
;             *(uint4*)(C + row * ldc + (bcol >> 1) + wc * 32 + fq * 8) = pack8(o);
;           }
;         }
;     }
;     if (!has_next) break;
; #pragma unroll
;     for (int a = 0; a < 2; ++a)
; #pragma unroll
;       for (int b = 0; b < 2; ++b)
; #pragma unroll
;         for (int m = 0; m < 4; ++m)
; #pragma unroll
;           for (int n = 0; n < 2; ++n) acc[a][b][m][n] = (f32x4){0.f, 0.f, 0.f, 0.f};
;     pm = npm; pn = npn; cA = nA; cB = nB; ++ui;
;   }
;   WAIT_V(0);
;   if (wr == 0) BAR;
;   BAR;
	v_mul_f32_e64 v57, v57, v49
	v_mul_f32_e64 v48, v58, v64
	v_mul_f32_e64 v49, v59, v65
	s_nop 0
	v_mul_f32_e64 v58, v48, v50
	v_mul_f32_e64 v59, v49, v51
	v_mul_f32_e32 v51, 0xbfb8aa3b, v44
	v_cvt_pk_bf16_f32 v48, v52, v53
	v_exp_f32_e32 v52, v51
	v_mul_f32_e32 v51, 0xbfb8aa3b, v45
	v_exp_f32_e32 v53, v51
	v_cvt_pk_bf16_f32 v49, v54, v55
	v_cvt_pk_bf16_f32 v50, v56, v57
	v_cvt_pk_bf16_f32 v51, v58, v59
	v_add_f32_e32 v52, 1.0, v52
	v_add_f32_e32 v53, 1.0, v53
	v_mad_i64_i32 v[54:55], s[18:19], v66, s44, v[142:143]
	v_rcp_f32_e32 v52, v52
	v_rcp_f32_e32 v53, v53
	global_store_dwordx4 v[54:55], v[48:51], off
	v_mul_f32_e64 v44, v44, v52
	v_mul_f32_e64 v45, v45, v53
	s_nop 0
	v_mul_f32_e32 v48, 0xbfb8aa3b, v46
	v_mul_f32_e32 v49, 0xbfb8aa3b, v47
	v_exp_f32_e32 v48, v48
	v_exp_f32_e32 v49, v49
	v_mul_f32_e64 v36, v44, v36
	v_mul_f32_e64 v37, v45, v37
	v_add_u32_e32 v50, 0x90, v149
	v_add_f32_e32 v44, 1.0, v48
	v_add_f32_e32 v45, 1.0, v49
	v_mul_f32_e32 v48, 0xbfb8aa3b, v40
	v_mul_f32_e32 v49, 0xbfb8aa3b, v41
	v_rcp_f32_e32 v44, v44
	v_rcp_f32_e32 v45, v45
	v_exp_f32_e32 v48, v48
	v_exp_f32_e32 v49, v49
	v_mul_f32_e64 v44, v46, v44
	v_mul_f32_e64 v45, v47, v45
	v_add_f32_e32 v46, 1.0, v48
	v_add_f32_e32 v47, 1.0, v49
	v_mul_f32_e32 v48, 0xbfb8aa3b, v42
	v_mul_f32_e32 v49, 0xbfb8aa3b, v43
	v_exp_f32_e32 v48, v48
	v_exp_f32_e32 v49, v49
	v_rcp_f32_e32 v46, v46
	v_rcp_f32_e32 v47, v47
	v_add_f32_e32 v48, 1.0, v48
	v_add_f32_e32 v49, 1.0, v49
	v_rcp_f32_e32 v48, v48
	v_rcp_f32_e32 v49, v49
	v_mul_f32_e64 v40, v40, v46
	v_mul_f32_e64 v41, v41, v47
	v_mul_f32_e64 v38, v44, v38
	v_mul_f32_e64 v39, v45, v39
	v_mul_f32_e64 v40, v40, v32
	v_mul_f32_e64 v41, v41, v33
	v_mul_f32_e64 v32, v42, v48
	v_mul_f32_e64 v33, v43, v49
	s_nop 0
	v_mul_f32_e64 v42, v32, v34
	v_mul_f32_e64 v43, v33, v35
	v_mul_f32_e32 v35, 0xbfb8aa3b, v28
	v_cvt_pk_bf16_f32 v32, v36, v37
	v_exp_f32_e32 v36, v35
	v_mul_f32_e32 v35, 0xbfb8aa3b, v29
	v_exp_f32_e32 v37, v35
	v_cvt_pk_bf16_f32 v33, v38, v39
	v_cvt_pk_bf16_f32 v34, v40, v41
	v_cvt_pk_bf16_f32 v35, v42, v43
	v_add_f32_e32 v36, 1.0, v36
	v_add_f32_e32 v37, 1.0, v37
	v_mad_i64_i32 v[38:39], s[18:19], v50, s44, v[142:143]
	v_rcp_f32_e32 v36, v36
	v_rcp_f32_e32 v37, v37
	global_store_dwordx4 v[38:39], v[32:35], off
	v_mul_f32_e64 v28, v28, v36
	v_mul_f32_e64 v29, v29, v37
	s_nop 0
	v_mul_f32_e32 v32, 0xbfb8aa3b, v30
	v_mul_f32_e32 v33, 0xbfb8aa3b, v31
	v_exp_f32_e32 v32, v32
	v_exp_f32_e32 v33, v33
	v_mul_f32_e64 v20, v28, v20
	v_mul_f32_e64 v21, v29, v21
	v_add_u32_e32 v34, 0xa0, v149
	v_add_f32_e32 v28, 1.0, v32
	v_add_f32_e32 v29, 1.0, v33
	v_mul_f32_e32 v32, 0xbfb8aa3b, v24
	v_mul_f32_e32 v33, 0xbfb8aa3b, v25
	v_rcp_f32_e32 v28, v28
	v_rcp_f32_e32 v29, v29
	v_exp_f32_e32 v32, v32
	v_exp_f32_e32 v33, v33
	v_mul_f32_e64 v28, v30, v28
	v_mul_f32_e64 v29, v31, v29
	v_add_f32_e32 v30, 1.0, v32
	v_add_f32_e32 v31, 1.0, v33
	v_mul_f32_e32 v32, 0xbfb8aa3b, v26
	v_mul_f32_e32 v33, 0xbfb8aa3b, v27
	v_exp_f32_e32 v32, v32
	v_exp_f32_e32 v33, v33
	v_rcp_f32_e32 v30, v30
	v_rcp_f32_e32 v31, v31
	v_add_f32_e32 v32, 1.0, v32
	v_add_f32_e32 v33, 1.0, v33
	v_rcp_f32_e32 v32, v32
	v_rcp_f32_e32 v33, v33
	v_mul_f32_e64 v24, v24, v30
	v_mul_f32_e64 v25, v25, v31
	v_mul_f32_e64 v22, v28, v22
	v_mul_f32_e64 v23, v29, v23
	v_mul_f32_e64 v24, v24, v16
	v_mul_f32_e64 v25, v25, v17
	v_mul_f32_e64 v16, v26, v32
	v_mul_f32_e64 v17, v27, v33
	s_nop 0
	v_mul_f32_e64 v26, v16, v18
	v_mul_f32_e64 v27, v17, v19
	v_mul_f32_e32 v19, 0xbfb8aa3b, v12
	v_cvt_pk_bf16_f32 v16, v20, v21
	v_exp_f32_e32 v20, v19
	v_mul_f32_e32 v19, 0xbfb8aa3b, v13
	v_exp_f32_e32 v21, v19
	v_cvt_pk_bf16_f32 v17, v22, v23
	v_cvt_pk_bf16_f32 v18, v24, v25
	v_cvt_pk_bf16_f32 v19, v26, v27
	v_add_f32_e32 v20, 1.0, v20
	v_add_f32_e32 v21, 1.0, v21
	v_mad_i64_i32 v[22:23], s[18:19], v34, s44, v[142:143]
	v_rcp_f32_e32 v20, v20
	v_rcp_f32_e32 v21, v21
	global_store_dwordx4 v[22:23], v[16:19], off
	v_mul_f32_e64 v12, v12, v20
	v_mul_f32_e64 v13, v13, v21
	s_nop 0
	v_mul_f32_e32 v16, 0xbfb8aa3b, v14
	v_mul_f32_e32 v17, 0xbfb8aa3b, v15
	v_exp_f32_e32 v16, v16
	v_exp_f32_e32 v17, v17
	v_mul_f32_e64 v4, v12, v4
	v_mul_f32_e64 v5, v13, v5
	v_add_u32_e32 v18, 0xb0, v149
	v_add_f32_e32 v12, 1.0, v16
	v_add_f32_e32 v13, 1.0, v17
	v_mul_f32_e32 v16, 0xbfb8aa3b, v8
	v_mul_f32_e32 v17, 0xbfb8aa3b, v9
	v_rcp_f32_e32 v12, v12
	v_rcp_f32_e32 v13, v13
	v_exp_f32_e32 v16, v16
	v_exp_f32_e32 v17, v17
	v_mul_f32_e64 v12, v14, v12
	v_mul_f32_e64 v13, v15, v13
	v_add_f32_e32 v14, 1.0, v16
	v_add_f32_e32 v15, 1.0, v17
	v_mul_f32_e32 v16, 0xbfb8aa3b, v10
	v_mul_f32_e32 v17, 0xbfb8aa3b, v11
	v_exp_f32_e32 v16, v16
	v_exp_f32_e32 v17, v17
	v_rcp_f32_e32 v14, v14
	v_rcp_f32_e32 v15, v15
	v_add_f32_e32 v16, 1.0, v16
	v_add_f32_e32 v17, 1.0, v17
	v_rcp_f32_e32 v16, v16
	v_rcp_f32_e32 v17, v17
	v_mul_f32_e64 v8, v8, v14
	v_mul_f32_e64 v9, v9, v15
	v_mul_f32_e64 v6, v12, v6
	v_mul_f32_e64 v7, v13, v7
	v_mul_f32_e64 v8, v8, v0
	v_mul_f32_e64 v9, v9, v1
	v_mul_f32_e64 v0, v10, v16
	v_mul_f32_e64 v1, v11, v17
	s_nop 0
	v_mul_f32_e64 v10, v0, v2
	v_mul_f32_e64 v11, v1, v3
	v_cvt_pk_bf16_f32 v0, v4, v5
	v_mad_i64_i32 v[4:5], s[18:19], v18, s44, v[142:143]
	v_cvt_pk_bf16_f32 v1, v6, v7
	v_cvt_pk_bf16_f32 v2, v8, v9
	v_cvt_pk_bf16_f32 v3, v10, v11
	s_mov_b64 s[18:19], s[14:15]
	global_store_dwordx4 v[4:5], v[0:3], off
	s_cbranch_vccz .LBB0_1023
	s_waitcnt vmcnt(0)
	s_cmpk_gt_u32 s26, 0xff
	s_cbranch_scc1 .LBB0_1030
	s_barrier
